# GEMM3: conv weights of the fused epilogue loaded once per tile instead of per row-group (8 dependent load waits removed); hand-style k-loop for mode 3; grid barrier non-leaders poll the top generation
# speedup vs baseline: 1.0358x; 1.0358x over previous
.LBB0_28:
	s_or_b64 exec, exec, s[38:39]
	v_cvt_f32_u32_e32 v5, v3
	s_waitcnt vmcnt(0)
	v_readfirstlane_b32 s2, v4
	v_sub_u32_e32 v4, 0, v3
	v_rcp_iflag_f32_e32 v5, v5
	v_add_u32_e32 v6, s2, v2
	v_mul_f32_e32 v5, 0x4f7ffffe, v5
	v_cvt_u32_f32_e32 v5, v5
	v_mul_lo_u32 v2, v4, v5
	v_mul_hi_u32 v2, v5, v2
	v_add_u32_e32 v2, v5, v2
	v_mul_hi_u32 v2, v6, v2
	v_mul_lo_u32 v4, v2, v3
	v_sub_u32_e32 v4, v6, v4
	v_add_u32_e32 v5, 1, v2
	v_sub_u32_e32 v7, v4, v3
	v_cmp_ge_u32_e32 vcc, v4, v3
	s_nop 1
	v_cndmask_b32_e32 v2, v2, v5, vcc
	v_cndmask_b32_e32 v4, v4, v7, vcc
	v_add_u32_e32 v5, 1, v2
	v_cmp_ge_u32_e32 vcc, v4, v3
	v_add_u32_e32 v4, 1, v6
	s_nop 0
	v_cndmask_b32_e32 v2, v2, v5, vcc
	v_mul_lo_u32 v5, v3, v2
	v_add_u32_e32 v3, v5, v3
	v_cmp_ne_u32_e32 vcc, v4, v3
	s_and_saveexec_b64 s[38:39], vcc
	s_xor_b64 s[38:39], exec, s[38:39]
	s_cbranch_execz .LBB0_42
	v_readlane_b32 s40, v240, 14
	v_readlane_b32 s41, v240, 15
	s_waitcnt lgkmcnt(0)
	s_nop 3
	global_load_dword v0, v1, s[40:41] sc1
	s_waitcnt vmcnt(0)
	v_cmp_eq_u32_e32 vcc, v0, v2
	s_and_saveexec_b64 s[40:41], vcc
	s_cbranch_execz .LBB0_41
	s_mov_b32 s2, 1
	s_mov_b64 s[42:43], 0
	s_branch .LBB0_32

.LBB0_34:
	v_readlane_b32 s46, v240, 14
	v_readlane_b32 s47, v240, 15
	s_add_i32 s2, s2, 1
	s_mov_b64 s[48:49], -1
	s_nop 2
	global_load_dword v0, v1, s[46:47] sc1
	s_waitcnt vmcnt(0)
	v_cmp_ne_u32_e32 vcc, v0, v2
	s_orn2_b64 s[46:47], vcc, exec
	s_branch .LBB0_31

.LBB0_159:
	s_andn2_b64 vcc, exec, s[0:1]
	s_cbranch_vccnz .LBB0_342
	v_readlane_b32 s0, v239, 54
	s_cmp_lt_i32 s0, 6
	s_mov_b64 s[0:1], -1
	s_cbranch_scc1 .LBB0_330
	v_readlane_b32 s0, v239, 54
	s_cmp_gt_i32 s0, 6
	s_mov_b64 s[0:1], -1
	s_cbranch_scc0 .LBB0_322
	v_mov_b32_e32 v2, v144
	s_mov_b32 s2, s91
	s_mov_b32 s91, s96
	s_cmpk_gt_i32 s2, 0x175f
	s_cbranch_scc1 .LBB0_321
	v_bfe_u32 v3, v2, 4, 2
	v_lshrrev_b32_e32 v0, 1, v2
	v_bitop3_b32 v5, v3, v0, 7 bitop3:0x78
	v_ashrrev_i32_e32 v7, 6, v2
	v_bfe_u32 v0, v2, 3, 3
	v_lshl_or_b32 v120, v7, 3, v0
	v_lshrrev_b32_e32 v10, 1, v120
	v_xor_b32_e32 v0, v10, v2
	v_lshlrev_b32_e32 v0, 4, v0
	v_readlane_b32 s0, v240, 22
	v_and_b32_e32 v8, 1, v7
	v_and_b32_e32 v0, 0x70, v0
	v_readlane_b32 s1, v240, 23
	v_bfe_u32 v4, v2, 1, 3
	v_and_b32_e32 v6, 15, v2
	v_ashrrev_i32_e32 v9, 7, v2
	v_lshl_add_u64 v[78:79], s[62:63], 0, v[0:1]
	v_lshl_add_u64 v[80:81], s[0:1], 0, v[0:1]
	v_lshl_add_u32 v121, v7, 10, 0
	v_lshlrev_b32_e32 v0, 7, v8
	v_lshlrev_b32_e32 v7, 5, v3
	v_readlane_b32 s0, v239, 53
	v_bitop3_b32 v4, v3, v4, 4 bitop3:0x36
	v_lshl_or_b32 v125, v9, 6, v6
	v_add3_u32 v7, 0, v0, v7
	s_mul_hi_i32 s39, s0, 0x8400
	s_mul_i32 s38, s0, 0x8400
	v_lshlrev_b32_e32 v0, 3, v3
	s_lshl_b32 s92, s0, 7
	s_movk_i32 s0, 0x110
	s_movk_i32 s5, 0x7d
	v_lshlrev_b32_e32 v119, 3, v4
	v_lshl_or_b32 v82, v8, 5, v0
	v_lshlrev_b32_e32 v127, 7, v6
	v_lshl_add_u32 v0, v4, 4, 0
	v_mul_lo_u32 v6, v125, s0
	v_cmp_eq_u32_e64 s[0:1], 0, v125
	v_add_u32_e32 v4, 0xffffff84, v125
	v_cmp_lt_u32_e32 vcc, s5, v125
	v_writelane_b32 v239, s0, 55
	v_lshlrev_b32_e32 v118, 3, v5
	v_cndmask_b32_e32 v4, -1, v4, vcc
	v_cmp_gt_i32_e32 vcc, 2, v125
	v_writelane_b32 v239, s1, 56
	v_cmp_eq_u32_e64 s[0:1], 1, v125
	v_cndmask_b32_e32 v4, v4, v125, vcc
	v_lshl_add_u32 v3, v5, 4, 0
	v_writelane_b32 v239, s0, 57
	v_lshlrev_b32_e32 v5, 1, v4
	s_movk_i32 s4, 0x1600
	v_writelane_b32 v239, s1, 58
	v_mad_u64_u32 v[84:85], s[0:1], v5, s4, 0
	v_cmp_lt_i32_e64 s[42:43], -1, v4
	v_cmp_gt_u32_e64 s[0:1], 2, v4
	v_mul_lo_u32 v86, v4, s79
	v_add_u32_e32 v4, 0, v6
	v_or_b32_e32 v134, 4, v82
	v_or_b32_e32 v129, 16, v125
	v_add_u32_e32 v5, 0xfffffef0, v4
	v_lshlrev_b32_e32 v12, 2, v82
	v_lshlrev_b32_e32 v13, 2, v134
	v_add_u32_e32 v132, v5, v12
	v_add_u32_e32 v135, v5, v13
	v_add_u32_e32 v5, 0xffffff94, v125
	v_cmp_lt_i32_e32 vcc, s5, v129
	v_lshlrev_b32_e32 v126, 13, v9
	v_writelane_b32 v239, s0, 59
	v_cndmask_b32_e32 v5, -1, v5, vcc
	v_cmp_gt_i32_e32 vcc, 0, v9
	v_writelane_b32 v239, s1, 60
	v_or_b32_e32 v130, 32, v125
	v_cndmask_b32_e32 v5, v5, v129, vcc
	v_lshlrev_b32_e32 v9, 1, v5
	v_mad_u64_u32 v[88:89], s[0:1], v9, s4, 0
	v_cmp_gt_u32_e64 s[0:1], 2, v5
	v_cmp_lt_i32_e64 s[46:47], -1, v5
	v_mul_lo_u32 v90, v5, s79
	v_writelane_b32 v239, s0, 61
	v_add_u32_e32 v5, 0xff0, v4
	v_add_u32_e32 v137, v5, v12
	v_writelane_b32 v239, s1, 62
	v_add_u32_e32 v139, v5, v13
	v_add_u32_e32 v5, 0xffffffa4, v125
	v_cmp_lt_i32_e64 s[0:1], s5, v130
	v_or_b32_e32 v131, 48, v125
	v_add_u32_e32 v9, 0xee0, v4
	v_cndmask_b32_e64 v5, -1, v5, s[0:1]
	v_cndmask_b32_e32 v5, v5, v130, vcc
	v_cmp_lt_i32_e64 s[50:51], -1, v5
	v_lshlrev_b32_e32 v5, 1, v5
	v_mad_u64_u32 v[92:93], s[0:1], v5, s4, 0
	v_add_u32_e32 v5, 0x20f0, v4
	v_add_u32_e32 v141, v5, v12
	v_add_u32_e32 v143, v5, v13
	v_add_u32_e32 v5, 0xffffffb4, v125
	v_cmp_lt_i32_e64 s[0:1], s5, v131
	v_add_u32_e32 v138, v9, v12
	v_add_u32_e32 v140, v9, v13
	v_cndmask_b32_e64 v5, -1, v5, s[0:1]
	v_add_u32_e32 v9, 0x1fe0, v4
	v_cndmask_b32_e32 v5, v5, v131, vcc
	v_add_u32_e32 v142, v9, v12
	v_add_u32_e32 v164, v9, v13
	v_lshlrev_b32_e32 v9, 1, v5
	v_mad_u64_u32 v[94:95], s[0:1], v9, s4, 0
	v_readlane_b32 s4, v240, 24
	v_readlane_b32 s16, v240, 36
	v_lshlrev_b32_e32 v128, 13, v8
	v_add_u32_e32 v11, 0xfffffde0, v4
	v_readlane_b32 s17, v240, 37
	s_add_u32 s38, s16, s38
	v_add_u32_e32 v133, v11, v12
	v_add_u32_e32 v136, v11, v13
	v_cmp_lt_i32_e64 s[52:53], -1, v5
	v_cmp_gt_u32_e64 s[0:1], 2, v5
	v_mul_lo_u32 v96, v5, s79
	v_add_u32_e32 v5, 0x31f0, v4
	v_add_u32_e32 v4, 0x30e0, v4
	v_add_u32_e32 v9, v0, v128
	v_add_u32_e32 v11, v0, v126
	s_addc_u32 s39, s17, s39
	v_lshlrev_b32_e32 v0, 6, v8
	v_add_u32_e32 v165, v5, v12
	v_add_u32_e32 v166, v4, v12
	v_add_u32_e32 v167, v5, v13
	v_add_u32_e32 v168, v4, v13
	s_add_u32 s40, s38, 0x2c00
	v_lshl_add_u64 v[4:5], s[30:31], 0, v[0:1]
	v_and_b32_e32 v0, 48, v2
	s_addc_u32 s41, s39, 0
	v_lshl_add_u64 v[98:99], v[4:5], 0, v[0:1]
	v_bitop3_b32 v0, v10, 7, v2 bitop3:0x48
	v_add_u32_e32 v12, v3, v128
	v_add_u32_e32 v3, v3, v126
	s_add_u32 s44, s38, 0x5800
	v_lshlrev_b32_e32 v0, 4, v0
	v_mov_b32_e32 v87, v1
	v_mov_b32_e32 v91, v1
	s_movk_i32 s90, 0x1600
	v_mov_b32_e32 v97, v1
	s_addc_u32 s45, s39, 0
	v_mov_b32_e32 v83, v1
	v_lshl_add_u64 v[100:101], s[26:27], 0, v[0:1]
	v_add_u32_e32 v169, v9, v127
	v_add_u32_e32 v170, v11, v127
	v_add_u32_e32 v171, v12, v127
	v_add_u32_e32 v172, v3, v127
	v_add_u32_e32 v173, v7, v6
	v_writelane_b32 v239, s0, 63
	v_readlane_b32 s5, v240, 25
	v_readlane_b32 s6, v240, 26
	v_writelane_b32 v238, s1, 0
	v_readlane_b32 s7, v240, 27
	v_readlane_b32 s8, v240, 28
	v_readlane_b32 s9, v240, 29
	v_readlane_b32 s10, v240, 30
	v_readlane_b32 s11, v240, 31
	v_readlane_b32 s12, v240, 32
	v_readlane_b32 s13, v240, 33
	v_readlane_b32 s14, v240, 34
	v_readlane_b32 s15, v240, 35
	v_readlane_b32 s18, v240, 38
	v_readlane_b32 s19, v240, 39
	v_lshrrev_b32_e32 v218, 1, v120
	v_xor_b32_e32 v218, v218, v144
	v_lshlrev_b32_e32 v218, 4, v218
	v_and_b32_e32 v218, 0x70, v218
	v_lshl_add_u32 v218, v120, 11, v218
	v_add_u32_e32 v219, 0x10000, v218
	v_add_u32_e32 v220, 0x20000, v218
	v_add_u32_e32 v221, 0x30000, v218
	v_lshlrev_b32_e32 v222, 1, v118
	v_add3_u32 v223, v222, v128, v127
	v_add3_u32 v222, v222, v126, v127
	v_lshlrev_b32_e32 v224, 1, v119
	v_add3_u32 v225, v224, v128, v127
	v_add3_u32 v224, v224, v126, v127
	v_readfirstlane_b32 s65, v121
	s_branch .LBB0_165
.LBB0_164:
	s_or_b64 exec, exec, s[0:1]
	s_waitcnt lgkmcnt(0)
	v_pk_mul_f32 v[26:27], v[26:27], v[42:43]
	s_add_i32 s2, s2, s91
	v_pk_fma_f32 v[26:27], v[30:31], v[34:35], v[26:27]
	s_movk_i32 s90, 0x1600
	s_nop 0
	v_pk_fma_f32 v[14:15], v[14:15], v[38:39], v[26:27]
	s_cmpk_gt_i32 s2, 0x175f
	v_mul_f32_e32 v0, 0xbfb8aa3b, v14
	v_exp_f32_e32 v26, v0
	v_mul_f32_e32 v0, 0xbfb8aa3b, v15
	v_exp_f32_e32 v27, v0
	s_nop 0
	v_pk_add_f32 v[26:27], v[26:27], 1.0 op_sel_hi:[1,0]
	s_nop 0
	v_div_scale_f32 v0, s[0:1], v27, v27, v15
	v_rcp_f32_e32 v30, v0
	s_nop 0
	v_fma_f32 v31, -v0, v30, 1.0
	v_fmac_f32_e32 v30, v31, v30
	v_div_scale_f32 v31, vcc, v15, v27, v15
	v_mul_f32_e32 v34, v31, v30
	v_fma_f32 v35, -v0, v34, v31
	v_fmac_f32_e32 v34, v35, v30
	v_fma_f32 v0, -v0, v34, v31
	v_div_fmas_f32 v0, v0, v30, v34
	v_div_fixup_f32 v15, v0, v27, v15
	v_div_scale_f32 v0, s[0:1], v26, v26, v14
	v_rcp_f32_e32 v27, v0
	s_nop 0
	v_fma_f32 v30, -v0, v27, 1.0
	v_fmac_f32_e32 v27, v30, v27
	v_div_scale_f32 v30, vcc, v14, v26, v14
	v_mul_f32_e32 v31, v30, v27
	v_fma_f32 v34, -v0, v31, v30
	v_fmac_f32_e32 v31, v34, v27
	v_fma_f32 v0, -v0, v31, v30
	v_div_fmas_f32 v0, v0, v27, v31
	v_div_fixup_f32 v14, v0, v26, v14
	v_pk_mul_f32 v[10:11], v[10:11], v[14:15]
	v_pk_mul_f32 v[14:15], v[28:29], v[44:45]
	v_cvt_pk_bf16_f32 v42, v10, v11
	v_pk_fma_f32 v[14:15], v[32:33], v[36:37], v[14:15]
	s_nop 0
	v_pk_fma_f32 v[14:15], v[16:17], v[40:41], v[14:15]
	s_nop 0
	v_mul_f32_e32 v0, 0xbfb8aa3b, v14
	v_exp_f32_e32 v16, v0
	v_mul_f32_e32 v0, 0xbfb8aa3b, v15
	v_exp_f32_e32 v17, v0
	s_nop 0
	v_pk_add_f32 v[16:17], v[16:17], 1.0 op_sel_hi:[1,0]
	s_nop 0
	v_div_scale_f32 v0, s[0:1], v17, v17, v15
	v_rcp_f32_e32 v26, v0
	s_nop 0
	v_fma_f32 v27, -v0, v26, 1.0
	v_fmac_f32_e32 v26, v27, v26
	v_div_scale_f32 v27, vcc, v15, v17, v15
	v_mul_f32_e32 v28, v27, v26
	v_fma_f32 v29, -v0, v28, v27
	v_fmac_f32_e32 v28, v29, v26
	v_fma_f32 v0, -v0, v28, v27
	v_div_fmas_f32 v0, v0, v26, v28
	v_div_fixup_f32 v15, v0, v17, v15
	v_div_scale_f32 v0, s[0:1], v16, v16, v14
	v_rcp_f32_e32 v17, v0
	s_nop 0
	v_fma_f32 v26, -v0, v17, 1.0
	v_fmac_f32_e32 v17, v26, v17
	v_div_scale_f32 v26, vcc, v14, v16, v14
	v_mul_f32_e32 v27, v26, v17
	v_fma_f32 v28, -v0, v27, v26
	v_fmac_f32_e32 v27, v28, v17
	v_fma_f32 v0, -v0, v27, v26
	v_div_fmas_f32 v0, v0, v17, v27
	v_div_fixup_f32 v14, v0, v16, v14
	v_pk_mul_f32 v[12:13], v[12:13], v[14:15]
	s_nop 0
	v_cvt_pk_bf16_f32 v43, v12, v13
	v_mov_b64_e32 v[10:11], v[242:243]
	v_mov_b64_e32 v[12:13], v[244:245]
	v_mov_b64_e32 v[14:15], v[246:247]
	v_mov_b64_e32 v[16:17], v[248:249]
	v_mov_b64_e32 v[26:27], v[250:251]
	v_mov_b64_e32 v[28:29], v[252:253]
	s_nop 0
	v_pk_mul_f32 v[14:15], v[18:19], v[14:15]
	s_nop 0
	v_pk_fma_f32 v[10:11], v[22:23], v[10:11], v[14:15]
	s_nop 0
	v_pk_fma_f32 v[6:7], v[6:7], v[26:27], v[10:11]
	s_nop 0
	v_mul_f32_e32 v0, 0xbfb8aa3b, v6
	v_exp_f32_e32 v10, v0
	v_mul_f32_e32 v0, 0xbfb8aa3b, v7
	v_exp_f32_e32 v11, v0
	s_nop 0
	v_pk_add_f32 v[10:11], v[10:11], 1.0 op_sel_hi:[1,0]
	s_nop 0
	v_div_scale_f32 v0, s[0:1], v11, v11, v7
	v_rcp_f32_e32 v14, v0
	s_nop 0
	v_fma_f32 v15, -v0, v14, 1.0
	v_fmac_f32_e32 v14, v15, v14
	v_div_scale_f32 v15, vcc, v7, v11, v7
	v_mul_f32_e32 v18, v15, v14
	v_fma_f32 v19, -v0, v18, v15
	v_fmac_f32_e32 v18, v19, v14
	v_fma_f32 v0, -v0, v18, v15
	v_div_fmas_f32 v0, v0, v14, v18
	v_div_fixup_f32 v7, v0, v11, v7
	v_div_scale_f32 v0, s[0:1], v10, v10, v6
	v_rcp_f32_e32 v11, v0
	s_nop 0
	v_fma_f32 v14, -v0, v11, 1.0
	v_fmac_f32_e32 v11, v14, v11
	v_div_scale_f32 v14, vcc, v6, v10, v6
	v_mul_f32_e32 v15, v14, v11
	v_fma_f32 v18, -v0, v15, v14
	v_fmac_f32_e32 v15, v18, v11
	v_fma_f32 v0, -v0, v15, v14
	v_div_fmas_f32 v0, v0, v11, v15
	v_div_fixup_f32 v6, v0, v10, v6
	v_pk_mul_f32 v[2:3], v[2:3], v[6:7]
	v_pk_mul_f32 v[6:7], v[20:21], v[16:17]
	v_cvt_pk_bf16_f32 v44, v2, v3
	v_pk_fma_f32 v[6:7], v[24:25], v[12:13], v[6:7]
	v_mad_i64_i32 v[2:3], s[0:1], v48, s76, v[102:103]
	v_pk_fma_f32 v[6:7], v[8:9], v[28:29], v[6:7]
	s_nop 0
	v_mul_f32_e32 v0, 0xbfb8aa3b, v6
	v_exp_f32_e32 v8, v0
	v_mul_f32_e32 v0, 0xbfb8aa3b, v7
	v_exp_f32_e32 v9, v0
	s_nop 0
	v_pk_add_f32 v[8:9], v[8:9], 1.0 op_sel_hi:[1,0]
	s_nop 0
	v_div_scale_f32 v0, s[0:1], v9, v9, v7
	v_rcp_f32_e32 v10, v0
	s_nop 0
	v_fma_f32 v11, -v0, v10, 1.0
	v_fmac_f32_e32 v10, v11, v10
	v_div_scale_f32 v11, vcc, v7, v9, v7
	v_mul_f32_e32 v12, v11, v10
	v_fma_f32 v13, -v0, v12, v11
	v_fmac_f32_e32 v12, v13, v10
	v_fma_f32 v0, -v0, v12, v11
	v_div_fmas_f32 v0, v0, v10, v12
	v_div_fixup_f32 v7, v0, v9, v7
	v_div_scale_f32 v0, s[0:1], v8, v8, v6
	v_rcp_f32_e32 v9, v0
	s_nop 0
	v_fma_f32 v10, -v0, v9, 1.0
	v_fmac_f32_e32 v9, v10, v9
	v_div_scale_f32 v10, vcc, v6, v8, v6
	v_mul_f32_e32 v11, v10, v9
	v_fma_f32 v12, -v0, v11, v10
	v_fmac_f32_e32 v11, v12, v9
	v_fma_f32 v0, -v0, v11, v10
	v_div_fmas_f32 v0, v0, v9, v11
	v_div_fixup_f32 v6, v0, v8, v6
	v_pk_mul_f32 v[4:5], v[4:5], v[6:7]
	s_nop 0
	v_cvt_pk_bf16_f32 v45, v4, v5
	global_store_dwordx4 v[2:3], v[42:45], off
	s_barrier
	s_cbranch_scc1 .LBB0_321
.LBB0_165:
	s_mul_hi_i32 s0, s2, 0x2e8ba2e9
	s_lshr_b32 s1, s0, 31
	s_ashr_i32 s48, s0, 3
	s_add_i32 s48, s48, s1
	s_lshl_b32 s97, s48, 7
	s_mul_i32 s0, s48, 44
	s_sub_i32 s54, s2, s0
	s_lshl_b32 s34, s97, 11
	s_add_u32 s34, s34, 0x1a40000
	s_add_u32 s34, s26, s34
	s_addc_u32 s35, s27, 0
	s_lshl_b32 s36, s54, 18
	s_add_u32 s36, s36, 0x9c0000
	s_add_u32 s36, s26, s36
	s_addc_u32 s37, s27, 0
	v_lshl_or_b32 v0, s54, 6, v82
	v_lshlrev_b32_e32 v0, 2, v0
	global_load_dwordx4 v[226:229], v0, s[38:39]
	global_load_dwordx4 v[230:233], v0, s[40:41]
	global_load_dwordx4 v[234:237], v0, s[44:45]
	global_load_dwordx4 v[242:245], v0, s[38:39] offset:16
	global_load_dwordx4 v[246:249], v0, s[40:41] offset:16
	global_load_dwordx4 v[250:253], v0, s[44:45] offset:16
	s_add_i32 m0, s65, 0x0
	s_nop 0
	global_load_lds_dwordx4 v218, s[34:35]
	s_add_i32 m0, s65, 0x4000
	s_nop 0
	global_load_lds_dwordx4 v218, s[36:37]
	s_add_i32 m0, s65, 0x1000
	s_nop 0
	global_load_lds_dwordx4 v219, s[34:35]
	s_add_i32 m0, s65, 0x5000
	s_nop 0
	global_load_lds_dwordx4 v219, s[36:37]
	s_add_i32 m0, s65, 0x2000
	s_nop 0
	global_load_lds_dwordx4 v220, s[34:35]
	s_add_i32 m0, s65, 0x6000
	s_nop 0
	global_load_lds_dwordx4 v220, s[36:37]
	s_add_i32 m0, s65, 0x3000
	s_nop 0
	global_load_lds_dwordx4 v221, s[34:35]
	s_add_i32 m0, s65, 0x7000
	s_nop 0
	global_load_lds_dwordx4 v221, s[36:37]
	s_add_u32 s34, s34, 0x80
	s_addc_u32 s35, s35, 0
	s_add_u32 s36, s36, 0x80
	s_addc_u32 s37, s37, 0
	v_mov_b32_e32 v52, 0
	s_mov_b32 s49, 0
	v_mov_b32_e32 v53, v52
	v_mov_b32_e32 v54, v52
	v_mov_b32_e32 v55, v52
	v_mov_b32_e32 v2, v52
	v_mov_b32_e32 v3, v52
	v_mov_b32_e32 v4, v52
	v_mov_b32_e32 v5, v52
	v_mov_b32_e32 v6, v52
	v_mov_b32_e32 v7, v52
	v_mov_b32_e32 v8, v52
	v_mov_b32_e32 v9, v52
	v_mov_b32_e32 v10, v52
	v_mov_b32_e32 v11, v52
	v_mov_b32_e32 v12, v52
	v_mov_b32_e32 v13, v52
	v_mov_b32_e32 v14, v52
	v_mov_b32_e32 v15, v52
	v_mov_b32_e32 v16, v52
	v_mov_b32_e32 v17, v52
	v_mov_b32_e32 v18, v52
	v_mov_b32_e32 v19, v52
	v_mov_b32_e32 v20, v52
	v_mov_b32_e32 v21, v52
	v_mov_b32_e32 v22, v52
	v_mov_b32_e32 v23, v52
	v_mov_b32_e32 v24, v52
	v_mov_b32_e32 v25, v52
	v_mov_b32_e32 v26, v52
	v_mov_b32_e32 v27, v52
	v_mov_b32_e32 v28, v52
	v_mov_b32_e32 v29, v52
	v_mov_b32_e32 v30, v52
	v_mov_b32_e32 v31, v52
	v_mov_b32_e32 v32, v52
	v_mov_b32_e32 v33, v52
	v_mov_b32_e32 v34, v52
	s_waitcnt lgkmcnt(0)
	v_mov_b32_e32 v35, v52
	v_mov_b32_e32 v36, v52
	v_mov_b32_e32 v37, v52
	v_mov_b32_e32 v38, v52
	v_mov_b32_e32 v39, v52
	v_mov_b32_e32 v40, v52
	v_mov_b32_e32 v41, v52
	v_mov_b32_e32 v44, v52
	v_mov_b32_e32 v45, v52
	v_mov_b32_e32 v46, v52
	v_mov_b32_e32 v47, v52
	v_mov_b32_e32 v48, v52
	v_mov_b32_e32 v49, v52
	v_mov_b32_e32 v50, v52
	v_mov_b32_e32 v51, v52
	v_mov_b32_e32 v56, v52
	v_mov_b32_e32 v57, v52
	v_mov_b32_e32 v58, v52
	v_mov_b32_e32 v59, v52
	v_mov_b32_e32 v60, v52
	v_mov_b32_e32 v61, v52
	v_mov_b32_e32 v62, v52
	v_mov_b32_e32 v63, v52
	v_mov_b32_e32 v64, v52
	v_mov_b32_e32 v65, v52
	v_mov_b32_e32 v66, v52
	v_mov_b32_e32 v67, v52
	s_mov_b32 s49, 0
.Lm3v2_loop:
	s_waitcnt vmcnt(0)
	s_barrier
	s_setprio 2
	s_add_i32 m0, s65, 0x8800
	ds_read_b128 v[72:75], v222
	global_load_lds_dwordx4 v218, s[34:35]
	ds_read_b128 v[102:105], v222 offset:2048
	s_add_i32 m0, s65, 0xc800
	ds_read_b128 v[106:109], v222 offset:4096
	global_load_lds_dwordx4 v218, s[36:37]
	ds_read_b128 v[110:113], v222 offset:6144
	s_add_i32 m0, s65, 0x9800
	ds_read_b128 v[114:117], v223 offset:16384
	global_load_lds_dwordx4 v219, s[34:35]
	ds_read_b128 v[174:177], v223 offset:18432
	s_add_i32 m0, s65, 0xd800
	ds_read_b128 v[178:181], v223 offset:20480
	global_load_lds_dwordx4 v219, s[36:37]
	ds_read_b128 v[182:185], v223 offset:22528
	s_add_i32 m0, s65, 0xa800
	ds_read_b128 v[186:189], v224
	global_load_lds_dwordx4 v220, s[34:35]
	ds_read_b128 v[190:193], v224 offset:2048
	s_add_i32 m0, s65, 0xe800
	ds_read_b128 v[194:197], v224 offset:4096
	global_load_lds_dwordx4 v220, s[36:37]
	ds_read_b128 v[198:201], v224 offset:6144
	s_add_i32 m0, s65, 0xb800
	ds_read_b128 v[202:205], v225 offset:16384
	global_load_lds_dwordx4 v221, s[34:35]
	ds_read_b128 v[206:209], v225 offset:18432
	s_add_i32 m0, s65, 0xf800
	ds_read_b128 v[210:213], v225 offset:20480
	global_load_lds_dwordx4 v221, s[36:37]
	ds_read_b128 v[214:217], v225 offset:22528
	s_add_u32 s34, s34, 0x80
	s_addc_u32 s35, s35, 0
	s_add_u32 s36, s36, 0x80
	s_addc_u32 s37, s37, 0
	s_setprio 0
	s_waitcnt lgkmcnt(8)
	v_mfma_f32_16x16x32_bf16 v[64:67], v[114:117], v[72:75], v[64:67]
	v_mfma_f32_16x16x32_bf16 v[60:63], v[174:177], v[72:75], v[60:63]
	v_mfma_f32_16x16x32_bf16 v[56:59], v[178:181], v[72:75], v[56:59]
	v_mfma_f32_16x16x32_bf16 v[48:51], v[182:185], v[72:75], v[48:51]
	v_mfma_f32_16x16x32_bf16 v[44:47], v[114:117], v[102:105], v[44:47]
	v_mfma_f32_16x16x32_bf16 v[38:41], v[174:177], v[102:105], v[38:41]
	v_mfma_f32_16x16x32_bf16 v[34:37], v[178:181], v[102:105], v[34:37]
	v_mfma_f32_16x16x32_bf16 v[30:33], v[182:185], v[102:105], v[30:33]
	v_mfma_f32_16x16x32_bf16 v[26:29], v[114:117], v[106:109], v[26:29]
	v_mfma_f32_16x16x32_bf16 v[22:25], v[174:177], v[106:109], v[22:25]
	v_mfma_f32_16x16x32_bf16 v[18:21], v[178:181], v[106:109], v[18:21]
	v_mfma_f32_16x16x32_bf16 v[14:17], v[182:185], v[106:109], v[14:17]
	v_mfma_f32_16x16x32_bf16 v[10:13], v[114:117], v[110:113], v[10:13]
	v_mfma_f32_16x16x32_bf16 v[6:9], v[174:177], v[110:113], v[6:9]
	v_mfma_f32_16x16x32_bf16 v[2:5], v[178:181], v[110:113], v[2:5]
	v_mfma_f32_16x16x32_bf16 v[52:55], v[182:185], v[110:113], v[52:55]
	s_waitcnt lgkmcnt(0)
	v_mfma_f32_16x16x32_bf16 v[64:67], v[202:205], v[186:189], v[64:67]
	v_mfma_f32_16x16x32_bf16 v[60:63], v[206:209], v[186:189], v[60:63]
	v_mfma_f32_16x16x32_bf16 v[56:59], v[210:213], v[186:189], v[56:59]
	v_mfma_f32_16x16x32_bf16 v[48:51], v[214:217], v[186:189], v[48:51]
	v_mfma_f32_16x16x32_bf16 v[44:47], v[202:205], v[190:193], v[44:47]
	v_mfma_f32_16x16x32_bf16 v[38:41], v[206:209], v[190:193], v[38:41]
	v_mfma_f32_16x16x32_bf16 v[34:37], v[210:213], v[190:193], v[34:37]
	v_mfma_f32_16x16x32_bf16 v[30:33], v[214:217], v[190:193], v[30:33]
	v_mfma_f32_16x16x32_bf16 v[26:29], v[202:205], v[194:197], v[26:29]
	v_mfma_f32_16x16x32_bf16 v[22:25], v[206:209], v[194:197], v[22:25]
	v_mfma_f32_16x16x32_bf16 v[18:21], v[210:213], v[194:197], v[18:21]
	v_mfma_f32_16x16x32_bf16 v[14:17], v[214:217], v[194:197], v[14:17]
	v_mfma_f32_16x16x32_bf16 v[10:13], v[202:205], v[198:201], v[10:13]
	v_mfma_f32_16x16x32_bf16 v[6:9], v[206:209], v[198:201], v[6:9]
	v_mfma_f32_16x16x32_bf16 v[2:5], v[210:213], v[198:201], v[2:5]
	v_mfma_f32_16x16x32_bf16 v[52:55], v[214:217], v[198:201], v[52:55]
	s_waitcnt vmcnt(0)
	s_barrier
	s_setprio 2
	s_add_i32 m0, s65, 0x0
	ds_read_b128 v[72:75], v222 offset:34816
	global_load_lds_dwordx4 v218, s[34:35]
	ds_read_b128 v[102:105], v222 offset:36864
	s_add_i32 m0, s65, 0x4000
	ds_read_b128 v[106:109], v222 offset:38912
	global_load_lds_dwordx4 v218, s[36:37]
	ds_read_b128 v[110:113], v222 offset:40960
	s_add_i32 m0, s65, 0x1000
	ds_read_b128 v[114:117], v223 offset:51200
	global_load_lds_dwordx4 v219, s[34:35]
	ds_read_b128 v[174:177], v223 offset:53248
	s_add_i32 m0, s65, 0x5000
	ds_read_b128 v[178:181], v223 offset:55296
	global_load_lds_dwordx4 v219, s[36:37]
	ds_read_b128 v[182:185], v223 offset:57344
	s_add_i32 m0, s65, 0x2000
	ds_read_b128 v[186:189], v224 offset:34816
	global_load_lds_dwordx4 v220, s[34:35]
	ds_read_b128 v[190:193], v224 offset:36864
	s_add_i32 m0, s65, 0x6000
	ds_read_b128 v[194:197], v224 offset:38912
	global_load_lds_dwordx4 v220, s[36:37]
	ds_read_b128 v[198:201], v224 offset:40960
	s_add_i32 m0, s65, 0x3000
	ds_read_b128 v[202:205], v225 offset:51200
	global_load_lds_dwordx4 v221, s[34:35]
	ds_read_b128 v[206:209], v225 offset:53248
	s_add_i32 m0, s65, 0x7000
	ds_read_b128 v[210:213], v225 offset:55296
	global_load_lds_dwordx4 v221, s[36:37]
	ds_read_b128 v[214:217], v225 offset:57344
	s_add_u32 s34, s34, 0x80
	s_addc_u32 s35, s35, 0
	s_add_u32 s36, s36, 0x80
	s_addc_u32 s37, s37, 0
	s_setprio 0
	s_waitcnt lgkmcnt(8)
	v_mfma_f32_16x16x32_bf16 v[64:67], v[114:117], v[72:75], v[64:67]
	v_mfma_f32_16x16x32_bf16 v[60:63], v[174:177], v[72:75], v[60:63]
	v_mfma_f32_16x16x32_bf16 v[56:59], v[178:181], v[72:75], v[56:59]
	v_mfma_f32_16x16x32_bf16 v[48:51], v[182:185], v[72:75], v[48:51]
	v_mfma_f32_16x16x32_bf16 v[44:47], v[114:117], v[102:105], v[44:47]
	v_mfma_f32_16x16x32_bf16 v[38:41], v[174:177], v[102:105], v[38:41]
	v_mfma_f32_16x16x32_bf16 v[34:37], v[178:181], v[102:105], v[34:37]
	v_mfma_f32_16x16x32_bf16 v[30:33], v[182:185], v[102:105], v[30:33]
	v_mfma_f32_16x16x32_bf16 v[26:29], v[114:117], v[106:109], v[26:29]
	v_mfma_f32_16x16x32_bf16 v[22:25], v[174:177], v[106:109], v[22:25]
	v_mfma_f32_16x16x32_bf16 v[18:21], v[178:181], v[106:109], v[18:21]
	v_mfma_f32_16x16x32_bf16 v[14:17], v[182:185], v[106:109], v[14:17]
	v_mfma_f32_16x16x32_bf16 v[10:13], v[114:117], v[110:113], v[10:13]
	v_mfma_f32_16x16x32_bf16 v[6:9], v[174:177], v[110:113], v[6:9]
	v_mfma_f32_16x16x32_bf16 v[2:5], v[178:181], v[110:113], v[2:5]
	v_mfma_f32_16x16x32_bf16 v[52:55], v[182:185], v[110:113], v[52:55]
	s_waitcnt lgkmcnt(0)
	v_mfma_f32_16x16x32_bf16 v[64:67], v[202:205], v[186:189], v[64:67]
	v_mfma_f32_16x16x32_bf16 v[60:63], v[206:209], v[186:189], v[60:63]
	v_mfma_f32_16x16x32_bf16 v[56:59], v[210:213], v[186:189], v[56:59]
	v_mfma_f32_16x16x32_bf16 v[48:51], v[214:217], v[186:189], v[48:51]
	v_mfma_f32_16x16x32_bf16 v[44:47], v[202:205], v[190:193], v[44:47]
	v_mfma_f32_16x16x32_bf16 v[38:41], v[206:209], v[190:193], v[38:41]
	v_mfma_f32_16x16x32_bf16 v[34:37], v[210:213], v[190:193], v[34:37]
	v_mfma_f32_16x16x32_bf16 v[30:33], v[214:217], v[190:193], v[30:33]
	v_mfma_f32_16x16x32_bf16 v[26:29], v[202:205], v[194:197], v[26:29]
	v_mfma_f32_16x16x32_bf16 v[22:25], v[206:209], v[194:197], v[22:25]
	v_mfma_f32_16x16x32_bf16 v[18:21], v[210:213], v[194:197], v[18:21]
	v_mfma_f32_16x16x32_bf16 v[14:17], v[214:217], v[194:197], v[14:17]
	v_mfma_f32_16x16x32_bf16 v[10:13], v[202:205], v[198:201], v[10:13]
	v_mfma_f32_16x16x32_bf16 v[6:9], v[206:209], v[198:201], v[6:9]
	v_mfma_f32_16x16x32_bf16 v[2:5], v[210:213], v[198:201], v[2:5]
	v_mfma_f32_16x16x32_bf16 v[52:55], v[214:217], v[198:201], v[52:55]
	s_add_u32 s49, s49, 1
	s_cmpk_lt_u32 s49, 7
	s_cbranch_scc1 .Lm3v2_loop
	s_waitcnt vmcnt(0)
	s_barrier
	s_setprio 2
	s_add_i32 m0, s65, 0x8800
	ds_read_b128 v[72:75], v222
	global_load_lds_dwordx4 v218, s[34:35]
	ds_read_b128 v[102:105], v222 offset:2048
	s_add_i32 m0, s65, 0xc800
	ds_read_b128 v[106:109], v222 offset:4096
	global_load_lds_dwordx4 v218, s[36:37]
	ds_read_b128 v[110:113], v222 offset:6144
	s_add_i32 m0, s65, 0x9800
	ds_read_b128 v[114:117], v223 offset:16384
	global_load_lds_dwordx4 v219, s[34:35]
	ds_read_b128 v[174:177], v223 offset:18432
	s_add_i32 m0, s65, 0xd800
	ds_read_b128 v[178:181], v223 offset:20480
	global_load_lds_dwordx4 v219, s[36:37]
	ds_read_b128 v[182:185], v223 offset:22528
	s_add_i32 m0, s65, 0xa800
	ds_read_b128 v[186:189], v224
	global_load_lds_dwordx4 v220, s[34:35]
	ds_read_b128 v[190:193], v224 offset:2048
	s_add_i32 m0, s65, 0xe800
	ds_read_b128 v[194:197], v224 offset:4096
	global_load_lds_dwordx4 v220, s[36:37]
	ds_read_b128 v[198:201], v224 offset:6144
	s_add_i32 m0, s65, 0xb800
	ds_read_b128 v[202:205], v225 offset:16384
	global_load_lds_dwordx4 v221, s[34:35]
	ds_read_b128 v[206:209], v225 offset:18432
	s_add_i32 m0, s65, 0xf800
	ds_read_b128 v[210:213], v225 offset:20480
	global_load_lds_dwordx4 v221, s[36:37]
	ds_read_b128 v[214:217], v225 offset:22528
	s_add_u32 s34, s34, 0x80
	s_addc_u32 s35, s35, 0
	s_add_u32 s36, s36, 0x80
	s_addc_u32 s37, s37, 0
	s_setprio 0
	s_waitcnt lgkmcnt(8)
	v_mfma_f32_16x16x32_bf16 v[64:67], v[114:117], v[72:75], v[64:67]
	v_mfma_f32_16x16x32_bf16 v[60:63], v[174:177], v[72:75], v[60:63]
	v_mfma_f32_16x16x32_bf16 v[56:59], v[178:181], v[72:75], v[56:59]
	v_mfma_f32_16x16x32_bf16 v[48:51], v[182:185], v[72:75], v[48:51]
	v_mfma_f32_16x16x32_bf16 v[44:47], v[114:117], v[102:105], v[44:47]
	v_mfma_f32_16x16x32_bf16 v[38:41], v[174:177], v[102:105], v[38:41]
	v_mfma_f32_16x16x32_bf16 v[34:37], v[178:181], v[102:105], v[34:37]
	v_mfma_f32_16x16x32_bf16 v[30:33], v[182:185], v[102:105], v[30:33]
	v_mfma_f32_16x16x32_bf16 v[26:29], v[114:117], v[106:109], v[26:29]
	v_mfma_f32_16x16x32_bf16 v[22:25], v[174:177], v[106:109], v[22:25]
	v_mfma_f32_16x16x32_bf16 v[18:21], v[178:181], v[106:109], v[18:21]
	v_mfma_f32_16x16x32_bf16 v[14:17], v[182:185], v[106:109], v[14:17]
	v_mfma_f32_16x16x32_bf16 v[10:13], v[114:117], v[110:113], v[10:13]
	v_mfma_f32_16x16x32_bf16 v[6:9], v[174:177], v[110:113], v[6:9]
	v_mfma_f32_16x16x32_bf16 v[2:5], v[178:181], v[110:113], v[2:5]
	v_mfma_f32_16x16x32_bf16 v[52:55], v[182:185], v[110:113], v[52:55]
	s_waitcnt lgkmcnt(0)
	v_mfma_f32_16x16x32_bf16 v[64:67], v[202:205], v[186:189], v[64:67]
	v_mfma_f32_16x16x32_bf16 v[60:63], v[206:209], v[186:189], v[60:63]
	v_mfma_f32_16x16x32_bf16 v[56:59], v[210:213], v[186:189], v[56:59]
	v_mfma_f32_16x16x32_bf16 v[48:51], v[214:217], v[186:189], v[48:51]
	v_mfma_f32_16x16x32_bf16 v[44:47], v[202:205], v[190:193], v[44:47]
	v_mfma_f32_16x16x32_bf16 v[38:41], v[206:209], v[190:193], v[38:41]
	v_mfma_f32_16x16x32_bf16 v[34:37], v[210:213], v[190:193], v[34:37]
	v_mfma_f32_16x16x32_bf16 v[30:33], v[214:217], v[190:193], v[30:33]
	v_mfma_f32_16x16x32_bf16 v[26:29], v[202:205], v[194:197], v[26:29]
	v_mfma_f32_16x16x32_bf16 v[22:25], v[206:209], v[194:197], v[22:25]
	v_mfma_f32_16x16x32_bf16 v[18:21], v[210:213], v[194:197], v[18:21]
	v_mfma_f32_16x16x32_bf16 v[14:17], v[214:217], v[194:197], v[14:17]
	v_mfma_f32_16x16x32_bf16 v[10:13], v[202:205], v[198:201], v[10:13]
	v_mfma_f32_16x16x32_bf16 v[6:9], v[206:209], v[198:201], v[6:9]
	v_mfma_f32_16x16x32_bf16 v[2:5], v[210:213], v[198:201], v[2:5]
	v_mfma_f32_16x16x32_bf16 v[52:55], v[214:217], v[198:201], v[52:55]
	s_waitcnt vmcnt(0) lgkmcnt(0)
	s_barrier
	s_setprio 2
	ds_read_b128 v[70:73], v169 offset:57344
	ds_read_b128 v[74:77], v169 offset:55296
	ds_read_b128 v[102:105], v169 offset:53248
	ds_read_b128 v[106:109], v169 offset:51200
	ds_read_b128 v[110:113], v170 offset:40960
	ds_read_b128 v[114:117], v170 offset:38912
	ds_read_b128 v[174:177], v170 offset:36864
	ds_read_b128 v[178:181], v170 offset:34816
	ds_read_b128 v[182:185], v171 offset:57344
	ds_read_b128 v[186:189], v171 offset:55296
	ds_read_b128 v[190:193], v171 offset:53248
	ds_read_b128 v[194:197], v171 offset:51200
	ds_read_b128 v[198:201], v172 offset:40960
	ds_read_b128 v[202:205], v172 offset:38912
	ds_read_b128 v[206:209], v172 offset:36864
	ds_read_b128 v[210:213], v172 offset:34816
	s_setprio 0
	s_waitcnt lgkmcnt(0)
	v_mfma_f32_16x16x32_bf16 v[64:67], v[194:197], v[210:213], v[64:67]
	s_waitcnt lgkmcnt(0)
	s_barrier
	v_mfma_f32_16x16x32_bf16 v[60:63], v[190:193], v[210:213], v[60:63]
	s_movk_i32 s0, 0x3fff
	v_mfma_f32_16x16x32_bf16 v[214:217], v[186:189], v[210:213], v[56:59]
	v_mfma_f32_16x16x32_bf16 v[48:51], v[182:185], v[210:213], v[48:51]
	v_mfma_f32_16x16x32_bf16 v[44:47], v[194:197], v[206:209], v[44:47]
	v_mfma_f32_16x16x32_bf16 v[38:41], v[190:193], v[206:209], v[38:41]
	v_mfma_f32_16x16x32_bf16 v[34:37], v[186:189], v[206:209], v[34:37]
	v_mfma_f32_16x16x32_bf16 v[30:33], v[182:185], v[206:209], v[30:33]
	v_mfma_f32_16x16x32_bf16 v[26:29], v[194:197], v[202:205], v[26:29]
	v_mfma_f32_16x16x32_bf16 v[22:25], v[190:193], v[202:205], v[22:25]
	v_mfma_f32_16x16x32_bf16 v[18:21], v[186:189], v[202:205], v[18:21]
	v_mfma_f32_16x16x32_bf16 v[14:17], v[182:185], v[202:205], v[14:17]
	v_mfma_f32_16x16x32_bf16 v[10:13], v[194:197], v[198:201], v[10:13]
	v_mfma_f32_16x16x32_bf16 v[6:9], v[190:193], v[198:201], v[6:9]
	v_mfma_f32_16x16x32_bf16 v[2:5], v[186:189], v[198:201], v[2:5]
	v_mfma_f32_16x16x32_bf16 v[182:185], v[182:185], v[198:201], v[52:55]
	v_mfma_f32_16x16x32_bf16 v[66:69], v[106:109], v[178:181], v[64:67]
	v_mfma_f32_16x16x32_bf16 v[58:61], v[102:105], v[178:181], v[60:63]
	v_mfma_f32_16x16x32_bf16 v[62:65], v[74:77], v[178:181], v[214:217]
	v_mfma_f32_16x16x32_bf16 v[54:57], v[70:73], v[178:181], v[48:51]
	v_mfma_f32_16x16x32_bf16 v[50:53], v[106:109], v[174:177], v[44:47]
	s_waitcnt vmcnt(0)
	s_nop 2
	ds_write_b128 v173, v[66:69]
	ds_write_b128 v173, v[58:61] offset:16
	s_nop 1
	ds_write_b128 v173, v[50:53] offset:4352
	v_mfma_f32_16x16x32_bf16 v[38:41], v[102:105], v[174:177], v[38:41]
	v_mfma_f32_16x16x32_bf16 v[46:49], v[74:77], v[174:177], v[34:37]
	v_mfma_f32_16x16x32_bf16 v[34:37], v[70:73], v[174:177], v[30:33]
	v_mfma_f32_16x16x32_bf16 v[30:33], v[106:109], v[114:117], v[26:29]
	v_mfma_f32_16x16x32_bf16 v[22:25], v[102:105], v[114:117], v[22:25]
	s_nop 3
	ds_write_b128 v173, v[38:41] offset:4368
	s_nop 1
	ds_write_b128 v173, v[30:33] offset:8704
	ds_write_b128 v173, v[22:25] offset:8720
	v_mfma_f32_16x16x32_bf16 v[26:29], v[74:77], v[114:117], v[18:21]
	v_mfma_f32_16x16x32_bf16 v[18:21], v[70:73], v[114:117], v[14:17]
	v_add_u32_e32 v114, s97, v125
	v_cmp_lt_i32_e64 s[56:57], s0, v114
	v_mfma_f32_16x16x32_bf16 v[14:17], v[106:109], v[110:113], v[10:13]
	v_mfma_f32_16x16x32_bf16 v[6:9], v[102:105], v[110:113], v[6:9]
	s_nop 6
	ds_write_b128 v173, v[14:17] offset:13056
	ds_write_b128 v173, v[6:9] offset:13072
	v_mfma_f32_16x16x32_bf16 v[10:13], v[74:77], v[110:113], v[2:5]
	s_waitcnt lgkmcnt(0)
	s_barrier
	v_mfma_f32_16x16x32_bf16 v[2:5], v[70:73], v[110:113], v[182:185]
	s_and_saveexec_b64 s[0:1], s[56:57]
	s_xor_b64 s[0:1], exec, s[0:1]
	v_add_u32_e32 v0, 0xffffc000, v114
	v_lshrrev_b32_e32 v44, 3, v0
	s_or_saveexec_b64 s[0:1], s[0:1]
	v_mov_b32_e32 v45, 0x80
	v_mov_b32_e32 v0, 6
	v_mov_b32_e32 v72, 7
	v_mov_b64_e32 v[70:71], 0x27bb440
	s_xor_b64 exec, exec, s[0:1]
	v_ashrrev_i32_e32 v44, 11, v114
	v_mov_b32_e32 v45, 8
	v_mov_b32_e32 v0, 0x7fe
	v_mov_b32_e32 v72, 0x7ff
	v_mov_b64_e32 v[70:71], 0x1255040
	s_or_b64 exec, exec, s[0:1]
	s_mul_hi_i32 s0, s48, 0xb000
	s_mul_i32 s48, s48, 0xb000
	v_readlane_b32 s4, v240, 60
	v_readlane_b32 s5, v240, 61
	s_add_u32 s48, s4, s48
	s_addc_u32 s49, s5, s0
	s_lshl_b32 s54, s54, 6
	v_lshl_add_u64 v[74:75], s[48:49], 0, v[86:87]
	s_mov_b64 s[0:1], 0x1600
	v_or_b32_e32 v104, s54, v82
	v_lshl_add_u64 v[102:103], s[48:49], 0, v[84:85]
	v_lshl_add_u64 v[76:77], v[74:75], 0, s[0:1]
	v_ashrrev_i32_e32 v105, 31, v104
	s_and_saveexec_b64 s[0:1], s[42:43]
	s_cbranch_execz .LBB0_174
	v_readlane_b32 s4, v239, 59
	v_cvt_pk_bf16_f32 v74, v66, v67
	v_cvt_pk_bf16_f32 v75, v68, v69
	v_lshl_add_u64 v[106:107], v[104:105], 1, v[102:103]
	v_readlane_b32 s5, v239, 60
	global_store_dwordx2 v[106:107], v[74:75], off
	s_and_b64 exec, exec, s[4:5]
	s_cbranch_execz .LBB0_174
	v_cvt_pk_bf16_f32 v74, v62, v63
	v_cvt_pk_bf16_f32 v75, v64, v65
	v_lshl_add_u64 v[106:107], v[104:105], 1, v[76:77]
	global_store_dwordx2 v[106:107], v[74:75], off

.LBB0_176:
	s_or_b64 exec, exec, s[0:1]
	v_readlane_b32 s4, v239, 55
	v_cmp_ne_u32_e32 vcc, 0, v72
	v_readlane_b32 s5, v239, 56
	s_and_b64 s[60:61], s[4:5], vcc
	v_readlane_b32 s4, v239, 57
	v_cmp_lt_u32_e32 vcc, 1, v72
	v_readlane_b32 s5, v239, 58
	v_add_u32_e32 v44, s92, v44
	s_and_b64 s[76:77], s[4:5], vcc
	v_ashrrev_i32_e32 v45, 31, v44
	v_mov_b32_e32 v73, v1
	s_nor_b64 s[76:77], s[60:61], s[76:77]
	v_mad_i64_i32 v[110:111], s[60:61], v44, s78, 0
	v_lshl_add_u64 v[44:45], v[44:45], 1, v[72:73]
	v_mad_u64_u32 v[74:75], s[60:61], v44, s79, 0
	v_cmp_eq_u32_e64 s[0:1], 0, v72
	v_cmp_gt_u32_e64 s[58:59], 2, v72
	v_mad_i32_i24 v75, v45, s79, v75
	s_and_saveexec_b64 s[78:79], s[76:77]
	s_cbranch_execz .LBB0_190
	s_and_saveexec_b64 s[60:61], s[0:1]
	s_xor_b64 s[60:61], exec, s[60:61]
	s_cbranch_execz .LBB0_181
	v_mov_b32_e32 v43, 0
	v_mov_b32_e32 v42, 0
	v_mov_b32_e32 v45, 0
	v_mov_b32_e32 v44, 0
	s_and_saveexec_b64 s[80:81], s[56:57]
	s_cbranch_execz .LBB0_180
	v_readlane_b32 s4, v240, 42
	v_readlane_b32 s5, v240, 43
	v_readlane_b32 s6, v240, 44
	v_readlane_b32 s7, v240, 45
	v_lshl_add_u64 v[42:43], s[4:5], 0, v[110:111]
	v_lshl_add_u64 v[42:43], v[104:105], 2, v[42:43]
	v_add_co_u32_e32 v42, vcc, 0x2000, v42
	v_readlane_b32 s8, v240, 46
	s_nop 0
	v_addc_co_u32_e32 v43, vcc, 0, v43, vcc
	global_load_dwordx4 v[42:45], v[42:43], off offset:3072 nt
	s_waitcnt vmcnt(0)
	v_readlane_b32 s9, v240, 47
	v_readlane_b32 s10, v240, 48
	v_readlane_b32 s11, v240, 49
	v_readlane_b32 s12, v240, 50
	v_readlane_b32 s13, v240, 51
	v_readlane_b32 s14, v240, 52
	v_readlane_b32 s15, v240, 53
	v_readlane_b32 s16, v240, 54
	v_readlane_b32 s17, v240, 55
	v_readlane_b32 s18, v240, 56
	v_readlane_b32 s19, v240, 57

.LBB0_182:
	s_nop 0
	ds_read_b128 v[42:45], v132
.LBB0_183:
	s_or_b64 exec, exec, s[60:61]
	s_and_saveexec_b64 s[60:61], s[58:59]
	s_xor_b64 s[60:61], exec, s[60:61]
	s_cbranch_execz .LBB0_187
	v_mov_b32_e32 v73, 0
	v_mov_b32_e32 v72, 0
	v_mov_b32_e32 v71, 0
	v_mov_b32_e32 v70, 0
	s_and_saveexec_b64 s[80:81], s[56:57]
	s_cbranch_execz .LBB0_186
	v_readlane_b32 s4, v240, 42
	v_readlane_b32 s5, v240, 43
	v_readlane_b32 s6, v240, 44
	v_readlane_b32 s7, v240, 45
	v_lshl_add_u64 v[70:71], s[4:5], 0, v[74:75]
	v_lshl_add_u64 v[70:71], v[104:105], 2, v[70:71]
	global_load_dwordx4 v[70:73], v[70:71], off nt
	s_waitcnt vmcnt(0)
	v_readlane_b32 s8, v240, 46
	v_readlane_b32 s9, v240, 47
	v_readlane_b32 s10, v240, 48
	v_readlane_b32 s11, v240, 49
	v_readlane_b32 s12, v240, 50
	v_readlane_b32 s13, v240, 51
	v_readlane_b32 s14, v240, 52
	v_readlane_b32 s15, v240, 53
	v_readlane_b32 s16, v240, 54
	v_readlane_b32 s17, v240, 55
	v_readlane_b32 s18, v240, 56
	v_readlane_b32 s19, v240, 57

.LBB0_188:
	s_nop 0
	ds_read_b128 v[70:73], v133
.LBB0_189:
	s_or_b64 exec, exec, s[60:61]
	v_lshlrev_b64 v[106:107], 2, v[104:105]
	v_lshl_add_u64 v[108:109], s[38:39], 0, v[106:107]
	v_lshl_add_u64 v[178:179], s[44:45], 0, v[106:107]
	v_lshl_add_u64 v[116:117], s[40:41], 0, v[106:107]
	v_mov_b64_e32 v[106:107], v[226:227]
	v_mov_b64_e32 v[108:109], v[228:229]
	s_nop 0
	v_mov_b64_e32 v[174:175], v[230:231]
	v_mov_b64_e32 v[176:177], v[232:233]
	s_nop 0
	v_mov_b64_e32 v[178:179], v[234:235]
	v_mov_b64_e32 v[180:181], v[236:237]
	s_waitcnt lgkmcnt(0)
	v_pk_mul_f32 v[42:43], v[42:43], v[174:175]
	s_nop 0
	v_pk_fma_f32 v[42:43], v[70:71], v[106:107], v[42:43]
	v_pk_mul_f32 v[44:45], v[44:45], v[176:177]
	s_nop 0
	v_pk_fma_f32 v[42:43], v[66:67], v[178:179], v[42:43]
	v_pk_fma_f32 v[44:45], v[72:73], v[108:109], v[44:45]
	v_mul_f32_e32 v66, 0xbfb8aa3b, v42
	v_mul_f32_e32 v67, 0xbfb8aa3b, v43
	v_exp_f32_e32 v66, v66
	v_exp_f32_e32 v67, v67
	v_pk_fma_f32 v[44:45], v[68:69], v[180:181], v[44:45]
	v_pk_add_f32 v[66:67], v[66:67], 1.0 op_sel_hi:[1,0]
	s_nop 0
	v_div_scale_f32 v70, s[60:61], v67, v67, v43
	v_rcp_f32_e32 v71, v70
	s_nop 0
	v_fma_f32 v106, -v70, v71, 1.0
	v_fmac_f32_e32 v71, v106, v71
	v_div_scale_f32 v106, vcc, v43, v67, v43
	v_mul_f32_e32 v107, v106, v71
	v_fma_f32 v115, -v70, v107, v106
	v_fmac_f32_e32 v107, v115, v71
	v_fma_f32 v70, -v70, v107, v106
	v_div_fmas_f32 v70, v70, v71, v107
	v_div_fixup_f32 v43, v70, v67, v43
	v_div_scale_f32 v67, s[60:61], v66, v66, v42
	v_rcp_f32_e32 v70, v67
	s_nop 0
	v_fma_f32 v71, -v67, v70, 1.0
	v_fmac_f32_e32 v70, v71, v70
	v_div_scale_f32 v71, vcc, v42, v66, v42
	v_mul_f32_e32 v106, v71, v70
	v_fma_f32 v107, -v67, v106, v71
	v_fmac_f32_e32 v106, v107, v70
	v_fma_f32 v67, -v67, v106, v71
	v_div_fmas_f32 v67, v67, v70, v106
	v_div_fixup_f32 v42, v67, v66, v42
	v_pk_mul_f32 v[42:43], v[62:63], v[42:43]
	v_mul_f32_e32 v62, 0xbfb8aa3b, v44
	v_mul_f32_e32 v63, 0xbfb8aa3b, v45
	v_exp_f32_e32 v62, v62
	v_exp_f32_e32 v63, v63
	v_cvt_pk_bf16_f32 v42, v42, v43
	v_pk_add_f32 v[62:63], v[62:63], 1.0 op_sel_hi:[1,0]
	s_nop 0
	v_div_scale_f32 v66, s[60:61], v63, v63, v45
	v_rcp_f32_e32 v67, v66
	s_nop 0
	v_fma_f32 v68, -v66, v67, 1.0
	v_fmac_f32_e32 v67, v68, v67
	v_div_scale_f32 v68, vcc, v45, v63, v45
	v_mul_f32_e32 v69, v68, v67
	v_fma_f32 v70, -v66, v69, v68
	v_fmac_f32_e32 v69, v70, v67
	v_fma_f32 v66, -v66, v69, v68
	v_div_fmas_f32 v66, v66, v67, v69
	v_div_fixup_f32 v45, v66, v63, v45
	v_div_scale_f32 v63, s[60:61], v62, v62, v44
	v_rcp_f32_e32 v66, v63
	s_nop 0
	v_fma_f32 v67, -v63, v66, 1.0
	v_fmac_f32_e32 v66, v67, v66
	v_div_scale_f32 v67, vcc, v44, v62, v44
	v_mul_f32_e32 v68, v67, v66
	v_fma_f32 v69, -v63, v68, v67
	v_fmac_f32_e32 v68, v69, v66
	v_fma_f32 v63, -v63, v68, v67
	v_div_fmas_f32 v63, v63, v66, v68
	v_div_fixup_f32 v44, v63, v62, v44
	v_pk_mul_f32 v[44:45], v[64:65], v[44:45]
	s_nop 0
	v_cvt_pk_bf16_f32 v43, v44, v45

.LBB0_195:
	s_or_b64 exec, exec, s[60:61]
	v_lshl_add_u64 v[102:103], s[54:55], 1, v[98:99]
	s_and_saveexec_b64 s[54:55], s[76:77]
	s_movk_i32 s78, 0x5800
	s_movk_i32 s79, 0x2c00
	s_cbranch_execz .LBB0_209
	s_and_saveexec_b64 s[60:61], s[0:1]
	s_xor_b64 s[0:1], exec, s[60:61]
	s_cbranch_execz .LBB0_200
	v_mov_b32_e32 v65, 0
	v_mov_b32_e32 v64, 0
	v_mov_b32_e32 v63, 0
	v_mov_b32_e32 v62, 0
	s_and_saveexec_b64 s[60:61], s[56:57]
	s_cbranch_execz .LBB0_199
	v_readlane_b32 s4, v240, 42
	v_readlane_b32 s5, v240, 43
	v_ashrrev_i32_e32 v109, 31, v108
	v_readlane_b32 s6, v240, 44
	v_lshl_add_u64 v[44:45], s[4:5], 0, v[110:111]
	v_lshl_add_u64 v[44:45], v[108:109], 2, v[44:45]
	v_add_co_u32_e32 v44, vcc, 0x2000, v44
	v_readlane_b32 s7, v240, 45
	s_nop 0
	v_addc_co_u32_e32 v45, vcc, 0, v45, vcc
	global_load_dwordx4 v[62:65], v[44:45], off offset:3072 nt
	s_waitcnt vmcnt(0)
	v_readlane_b32 s8, v240, 46
	v_readlane_b32 s9, v240, 47
	v_readlane_b32 s10, v240, 48
	v_readlane_b32 s11, v240, 49
	v_readlane_b32 s12, v240, 50
	v_readlane_b32 s13, v240, 51
	v_readlane_b32 s14, v240, 52
	v_readlane_b32 s15, v240, 53
	v_readlane_b32 s16, v240, 54
	v_readlane_b32 s17, v240, 55
	v_readlane_b32 s18, v240, 56
	v_readlane_b32 s19, v240, 57

.LBB0_201:
	s_nop 0
	ds_read_b128 v[62:65], v135
.LBB0_202:
	s_or_b64 exec, exec, s[0:1]
	s_and_saveexec_b64 s[0:1], s[58:59]
	s_xor_b64 s[0:1], exec, s[0:1]
	s_cbranch_execz .LBB0_206
	v_mov_b32_e32 v69, 0
	v_mov_b32_e32 v68, 0
	v_mov_b32_e32 v67, 0
	v_mov_b32_e32 v66, 0
	s_and_saveexec_b64 s[58:59], s[56:57]
	s_cbranch_execz .LBB0_205
	v_readlane_b32 s4, v240, 42
	v_readlane_b32 s5, v240, 43
	v_readlane_b32 s6, v240, 44
	v_readlane_b32 s7, v240, 45
	v_lshl_add_u64 v[44:45], s[4:5], 0, v[74:75]
	v_lshl_add_u64 v[44:45], v[106:107], 2, v[44:45]
	global_load_dwordx4 v[66:69], v[44:45], off offset:16 nt
	s_waitcnt vmcnt(0)
	v_readlane_b32 s8, v240, 46
	v_readlane_b32 s9, v240, 47
	v_readlane_b32 s10, v240, 48
	v_readlane_b32 s11, v240, 49
	v_readlane_b32 s12, v240, 50
	v_readlane_b32 s13, v240, 51
	v_readlane_b32 s14, v240, 52
	v_readlane_b32 s15, v240, 53
	v_readlane_b32 s16, v240, 54
	v_readlane_b32 s17, v240, 55
	v_readlane_b32 s18, v240, 56
	v_readlane_b32 s19, v240, 57

.LBB0_207:
	s_nop 0
	ds_read_b128 v[66:69], v136
.LBB0_208:
	s_or_b64 exec, exec, s[0:1]
	v_ashrrev_i32_e32 v109, 31, v108
	v_lshlrev_b64 v[70:71], 2, v[108:109]
	v_lshl_add_u64 v[44:45], v[106:107], 2, s[38:39]
	v_lshl_add_u64 v[74:75], s[40:41], 0, v[70:71]
	v_lshl_add_u64 v[110:111], s[44:45], 0, v[70:71]
	v_mov_b64_e32 v[70:71], v[242:243]
	v_mov_b64_e32 v[72:73], v[244:245]
	s_nop 0
	v_mov_b64_e32 v[74:75], v[246:247]
	v_mov_b64_e32 v[76:77], v[248:249]
	s_waitcnt lgkmcnt(0)
	v_pk_mul_f32 v[44:45], v[64:65], v[76:77]
	v_mov_b64_e32 v[110:111], v[250:251]
	v_mov_b64_e32 v[112:113], v[252:253]
	v_pk_fma_f32 v[44:45], v[68:69], v[72:73], v[44:45]
	s_nop 0
	v_pk_fma_f32 v[44:45], v[60:61], v[112:113], v[44:45]
	s_nop 0
	v_mul_f32_e32 v0, 0xbfb8aa3b, v44
	v_exp_f32_e32 v60, v0
	v_mul_f32_e32 v0, 0xbfb8aa3b, v45
	v_exp_f32_e32 v61, v0
	s_nop 0
	v_pk_add_f32 v[60:61], v[60:61], 1.0 op_sel_hi:[1,0]
	s_nop 0
	v_div_scale_f32 v0, s[0:1], v61, v61, v45
	v_rcp_f32_e32 v64, v0
	s_nop 0
	v_fma_f32 v65, -v0, v64, 1.0
	v_fmac_f32_e32 v64, v65, v64
	v_div_scale_f32 v65, vcc, v45, v61, v45
	v_mul_f32_e32 v68, v65, v64
	v_fma_f32 v69, -v0, v68, v65
	v_fmac_f32_e32 v68, v69, v64
	v_fma_f32 v0, -v0, v68, v65
	v_div_fmas_f32 v0, v0, v64, v68
	v_div_fixup_f32 v45, v0, v61, v45
	v_div_scale_f32 v0, s[0:1], v60, v60, v44
	v_rcp_f32_e32 v61, v0
	s_nop 0
	v_fma_f32 v64, -v0, v61, 1.0
	v_fmac_f32_e32 v61, v64, v61
	v_div_scale_f32 v64, vcc, v44, v60, v44
	v_mul_f32_e32 v65, v64, v61
	v_fma_f32 v68, -v0, v65, v64
	v_fmac_f32_e32 v65, v68, v61
	v_fma_f32 v0, -v0, v65, v64
	v_div_fmas_f32 v0, v0, v61, v65
	v_div_fixup_f32 v44, v0, v60, v44
	v_pk_mul_f32 v[44:45], v[56:57], v[44:45]
	v_pk_mul_f32 v[56:57], v[62:63], v[74:75]
	v_cvt_pk_bf16_f32 v45, v44, v45
	v_pk_fma_f32 v[56:57], v[66:67], v[70:71], v[56:57]
	s_nop 0
	v_pk_fma_f32 v[56:57], v[58:59], v[110:111], v[56:57]
	s_nop 0
	v_mul_f32_e32 v0, 0xbfb8aa3b, v56
	v_exp_f32_e32 v58, v0
	v_mul_f32_e32 v0, 0xbfb8aa3b, v57
	v_exp_f32_e32 v59, v0
	s_nop 0
	v_pk_add_f32 v[58:59], v[58:59], 1.0 op_sel_hi:[1,0]
	s_nop 0
	v_div_scale_f32 v0, s[0:1], v59, v59, v57
	v_rcp_f32_e32 v44, v0
	s_nop 0
	v_fma_f32 v60, -v0, v44, 1.0
	v_fmac_f32_e32 v44, v60, v44
	v_div_scale_f32 v60, vcc, v57, v59, v57
	v_mul_f32_e32 v61, v60, v44
	v_fma_f32 v62, -v0, v61, v60
	v_fmac_f32_e32 v61, v62, v44
	v_fma_f32 v0, -v0, v61, v60
	v_div_fmas_f32 v0, v0, v44, v61
	v_div_fixup_f32 v57, v0, v59, v57
	v_div_scale_f32 v0, s[0:1], v58, v58, v56
	v_rcp_f32_e32 v44, v0
	s_nop 0
	v_fma_f32 v59, -v0, v44, 1.0
	v_fmac_f32_e32 v44, v59, v44
	v_div_scale_f32 v59, vcc, v56, v58, v56
	v_mul_f32_e32 v60, v59, v44
	v_fma_f32 v61, -v0, v60, v59
	v_fmac_f32_e32 v60, v61, v44
	v_fma_f32 v0, -v0, v60, v59
	v_div_fmas_f32 v0, v0, v44, v60
	v_div_fixup_f32 v56, v0, v58, v56
	v_pk_mul_f32 v[54:55], v[54:55], v[56:57]
	s_nop 0
	v_cvt_pk_bf16_f32 v44, v54, v55
	v_mad_i64_i32 v[54:55], s[0:1], v114, s90, v[102:103]
	global_store_dwordx4 v[54:55], v[42:45], off

.LBB0_218:
	s_or_b64 exec, exec, s[56:57]
	v_cmp_ne_u32_e64 s[56:57], 0, v62
	s_and_saveexec_b64 s[58:59], s[56:57]
	s_xor_b64 s[58:59], exec, s[58:59]
	ds_read_b128 v[58:61], v137
	s_or_saveexec_b64 s[58:59], s[58:59]
	v_add_u32_e32 v64, s92, v54
	v_mad_i64_i32 v[54:55], s[60:61], v64, s78, 0
	s_xor_b64 exec, exec, s[58:59]
	s_cbranch_execz .LBB0_224
	s_waitcnt lgkmcnt(0)
	v_mov_b32_e32 v59, 0
	v_mov_b32_e32 v58, 0
	v_mov_b32_e32 v61, 0
	v_mov_b32_e32 v60, 0
	s_and_saveexec_b64 s[60:61], s[0:1]
	s_cbranch_execz .LBB0_223
	v_readlane_b32 s4, v240, 42
	v_readlane_b32 s5, v240, 43
	v_readlane_b32 s6, v240, 44
	v_readlane_b32 s7, v240, 45
	v_lshl_add_u64 v[58:59], s[4:5], 0, v[54:55]
	v_lshl_add_u64 v[58:59], v[104:105], 2, v[58:59]
	v_add_co_u32_e32 v58, vcc, 0x2000, v58
	v_readlane_b32 s8, v240, 46
	s_nop 0
	v_addc_co_u32_e32 v59, vcc, 0, v59, vcc
	global_load_dwordx4 v[58:61], v[58:59], off offset:3072 nt
	s_waitcnt vmcnt(0)
	v_readlane_b32 s9, v240, 47
	v_readlane_b32 s10, v240, 48
	v_readlane_b32 s11, v240, 49
	v_readlane_b32 s12, v240, 50
	v_readlane_b32 s13, v240, 51
	v_readlane_b32 s14, v240, 52
	v_readlane_b32 s15, v240, 53
	v_readlane_b32 s16, v240, 54
	v_readlane_b32 s17, v240, 55
	v_readlane_b32 s18, v240, 56
	v_readlane_b32 s19, v240, 57

.LBB0_224:
	s_or_b64 exec, exec, s[58:59]
	v_ashrrev_i32_e32 v65, 31, v64
	v_mov_b32_e32 v63, v1
	v_cmp_gt_u32_e64 s[58:59], 2, v62
	v_lshl_add_u64 v[62:63], v[64:65], 1, v[62:63]
	v_mad_u64_u32 v[116:117], s[60:61], v62, s79, 0
	v_mad_i32_i24 v117, v63, s79, v117
	s_and_saveexec_b64 s[60:61], s[58:59]
	s_xor_b64 s[60:61], exec, s[60:61]
	s_cbranch_execz .LBB0_228
	v_mov_b32_e32 v65, 0
	v_mov_b32_e32 v64, 0
	v_mov_b32_e32 v63, 0
	v_mov_b32_e32 v62, 0
	s_and_saveexec_b64 s[74:75], s[0:1]
	s_cbranch_execz .LBB0_227
	v_readlane_b32 s4, v240, 42
	v_readlane_b32 s5, v240, 43
	v_readlane_b32 s6, v240, 44
	v_readlane_b32 s7, v240, 45
	v_lshl_add_u64 v[62:63], s[4:5], 0, v[116:117]
	v_lshl_add_u64 v[62:63], v[104:105], 2, v[62:63]
	global_load_dwordx4 v[62:65], v[62:63], off nt
	s_waitcnt vmcnt(0)
	v_readlane_b32 s8, v240, 46
	v_readlane_b32 s9, v240, 47
	v_readlane_b32 s10, v240, 48
	v_readlane_b32 s11, v240, 49
	v_readlane_b32 s12, v240, 50
	v_readlane_b32 s13, v240, 51
	v_readlane_b32 s14, v240, 52
	v_readlane_b32 s15, v240, 53
	v_readlane_b32 s16, v240, 54
	v_readlane_b32 s17, v240, 55
	v_readlane_b32 s18, v240, 56
	v_readlane_b32 s19, v240, 57

.LBB0_228:
	s_andn2_saveexec_b64 s[60:61], s[60:61]
	s_cbranch_execz .LBB0_230
	s_nop 0
	ds_read_b128 v[62:65], v138
.LBB0_230:
	s_or_b64 exec, exec, s[60:61]
	v_lshlrev_b64 v[66:67], 2, v[104:105]
	v_lshl_add_u64 v[110:111], s[38:39], 0, v[66:67]
	v_lshl_add_u64 v[112:113], s[40:41], 0, v[66:67]
	v_lshl_add_u64 v[114:115], s[44:45], 0, v[66:67]
	v_mov_b64_e32 v[66:67], v[226:227]
	v_mov_b64_e32 v[68:69], v[228:229]
	v_mov_b64_e32 v[74:75], v[230:231]
	v_mov_b64_e32 v[76:77], v[232:233]
	v_mov_b64_e32 v[70:71], v[234:235]
	v_mov_b64_e32 v[72:73], v[236:237]
	s_and_saveexec_b64 s[60:61], s[46:47]
	s_cbranch_execz .LBB0_233
	v_readlane_b32 s4, v239, 61
	v_cvt_pk_bf16_f32 v176, v38, v39
	v_cvt_pk_bf16_f32 v177, v40, v41
	v_lshl_add_u64 v[44:45], v[106:107], 1, v[44:45]
	v_readlane_b32 s5, v239, 62
	global_store_dwordx2 v[44:45], v[176:177], off offset:8
	s_and_b64 exec, exec, s[4:5]
	s_cbranch_execz .LBB0_233
	v_ashrrev_i32_e32 v109, 31, v108
	v_cvt_pk_bf16_f32 v44, v34, v35
	v_cvt_pk_bf16_f32 v45, v36, v37
	v_lshl_add_u64 v[42:43], v[108:109], 1, v[42:43]
	global_store_dwordx2 v[42:43], v[44:45], off

.LBB0_238:
	v_mov_b32_e32 v57, 0
	v_mov_b32_e32 v56, 0
	v_mov_b32_e32 v55, 0
	v_mov_b32_e32 v54, 0
	s_and_saveexec_b64 s[56:57], s[0:1]
	s_cbranch_execz .LBB0_240
	v_readlane_b32 s4, v240, 42
	v_readlane_b32 s5, v240, 43
	v_readlane_b32 s6, v240, 44
	v_readlane_b32 s7, v240, 45
	v_lshl_add_u64 v[54:55], s[4:5], 0, v[116:117]
	v_lshl_add_u64 v[54:55], v[106:107], 2, v[54:55]
	global_load_dwordx4 v[54:57], v[54:55], off offset:16 nt
	s_waitcnt vmcnt(0)
	v_readlane_b32 s8, v240, 46
	v_readlane_b32 s9, v240, 47
	v_readlane_b32 s10, v240, 48
	v_readlane_b32 s11, v240, 49
	v_readlane_b32 s12, v240, 50
	v_readlane_b32 s13, v240, 51
	v_readlane_b32 s14, v240, 52
	v_readlane_b32 s15, v240, 53
	v_readlane_b32 s16, v240, 54
	v_readlane_b32 s17, v240, 55
	v_readlane_b32 s18, v240, 56
	v_readlane_b32 s19, v240, 57

.LBB0_242:
	s_waitcnt lgkmcnt(0)
	v_mov_b32_e32 v43, 0
	v_mov_b32_e32 v42, 0
	v_mov_b32_e32 v45, 0
	v_mov_b32_e32 v44, 0
	s_and_saveexec_b64 s[56:57], s[0:1]
	s_cbranch_execz .LBB0_244
	v_readlane_b32 s4, v240, 42
	v_readlane_b32 s5, v240, 43
	v_ashrrev_i32_e32 v109, 31, v108
	v_readlane_b32 s6, v240, 44
	v_lshl_add_u64 v[42:43], s[4:5], 0, v[54:55]
	v_lshl_add_u64 v[42:43], v[108:109], 2, v[42:43]
	v_add_co_u32_e32 v42, vcc, 0x2000, v42
	v_readlane_b32 s7, v240, 45
	s_nop 0
	v_addc_co_u32_e32 v43, vcc, 0, v43, vcc
	global_load_dwordx4 v[42:45], v[42:43], off offset:3072 nt
	s_waitcnt vmcnt(0)
	v_readlane_b32 s8, v240, 46
	v_readlane_b32 s9, v240, 47
	v_readlane_b32 s10, v240, 48
	v_readlane_b32 s11, v240, 49
	v_readlane_b32 s12, v240, 50
	v_readlane_b32 s13, v240, 51
	v_readlane_b32 s14, v240, 52
	v_readlane_b32 s15, v240, 53
	v_readlane_b32 s16, v240, 54
	v_readlane_b32 s17, v240, 55
	v_readlane_b32 s18, v240, 56
	v_readlane_b32 s19, v240, 57

.LBB0_246:
	s_nop 0
	ds_read_b128 v[54:57], v140
.LBB0_247:
	s_or_b64 exec, exec, s[0:1]
	s_waitcnt lgkmcnt(0)
	v_pk_mul_f32 v[58:59], v[58:59], v[74:75]
	v_ashrrev_i32_e32 v109, 31, v108
	v_pk_fma_f32 v[58:59], v[62:63], v[66:67], v[58:59]
	s_nop 0
	v_pk_fma_f32 v[50:51], v[50:51], v[70:71], v[58:59]
	v_lshl_add_u64 v[70:71], v[106:107], 2, s[38:39]
	v_mul_f32_e32 v0, 0xbfb8aa3b, v50
	v_exp_f32_e32 v58, v0
	v_mul_f32_e32 v0, 0xbfb8aa3b, v51
	v_exp_f32_e32 v59, v0
	s_nop 0
	v_pk_add_f32 v[58:59], v[58:59], 1.0 op_sel_hi:[1,0]
	s_nop 0
	v_div_scale_f32 v0, s[0:1], v59, v59, v51
	v_rcp_f32_e32 v62, v0
	s_nop 0
	v_fma_f32 v63, -v0, v62, 1.0
	v_fmac_f32_e32 v62, v63, v62
	v_div_scale_f32 v63, vcc, v51, v59, v51
	v_mul_f32_e32 v66, v63, v62
	v_fma_f32 v67, -v0, v66, v63
	v_fmac_f32_e32 v66, v67, v62
	v_fma_f32 v0, -v0, v66, v63
	v_div_fmas_f32 v0, v0, v62, v66
	v_div_fixup_f32 v51, v0, v59, v51
	v_div_scale_f32 v0, s[0:1], v58, v58, v50
	v_rcp_f32_e32 v59, v0
	s_nop 0
	v_fma_f32 v62, -v0, v59, 1.0
	v_fmac_f32_e32 v59, v62, v59
	v_div_scale_f32 v62, vcc, v50, v58, v50
	v_mul_f32_e32 v63, v62, v59
	v_fma_f32 v66, -v0, v63, v62
	v_fmac_f32_e32 v63, v66, v59
	v_fma_f32 v0, -v0, v63, v62
	v_div_fmas_f32 v0, v0, v59, v63
	v_div_fixup_f32 v50, v0, v58, v50
	v_pk_mul_f32 v[46:47], v[46:47], v[50:51]
	v_pk_mul_f32 v[50:51], v[60:61], v[76:77]
	v_cvt_pk_bf16_f32 v46, v46, v47
	v_pk_fma_f32 v[50:51], v[64:65], v[68:69], v[50:51]
	s_nop 0
	v_pk_fma_f32 v[50:51], v[52:53], v[72:73], v[50:51]
	s_nop 0
	v_mul_f32_e32 v0, 0xbfb8aa3b, v50
	v_exp_f32_e32 v52, v0
	v_mul_f32_e32 v0, 0xbfb8aa3b, v51
	v_exp_f32_e32 v53, v0
	s_nop 0
	v_pk_add_f32 v[52:53], v[52:53], 1.0 op_sel_hi:[1,0]
	s_nop 0
	v_div_scale_f32 v0, s[0:1], v53, v53, v51
	v_rcp_f32_e32 v58, v0
	s_nop 0
	v_fma_f32 v59, -v0, v58, 1.0
	v_fmac_f32_e32 v58, v59, v58
	v_div_scale_f32 v59, vcc, v51, v53, v51
	v_mul_f32_e32 v60, v59, v58
	v_fma_f32 v61, -v0, v60, v59
	v_fmac_f32_e32 v60, v61, v58
	v_fma_f32 v0, -v0, v60, v59
	v_div_fmas_f32 v0, v0, v58, v60
	v_div_fixup_f32 v51, v0, v53, v51
	v_div_scale_f32 v0, s[0:1], v52, v52, v50
	v_rcp_f32_e32 v53, v0
	s_nop 0
	v_fma_f32 v58, -v0, v53, 1.0
	v_fmac_f32_e32 v53, v58, v53
	v_div_scale_f32 v58, vcc, v50, v52, v50
	v_mul_f32_e32 v59, v58, v53
	v_fma_f32 v60, -v0, v59, v58
	v_fmac_f32_e32 v59, v60, v53
	v_fma_f32 v0, -v0, v59, v58
	v_div_fmas_f32 v0, v0, v53, v59
	v_div_fixup_f32 v50, v0, v52, v50
	v_pk_mul_f32 v[48:49], v[48:49], v[50:51]
	s_nop 0
	v_cvt_pk_bf16_f32 v47, v48, v49
	v_lshlrev_b64 v[48:49], 2, v[108:109]
	v_lshl_add_u64 v[68:69], s[40:41], 0, v[48:49]
	v_lshl_add_u64 v[66:67], s[44:45], 0, v[48:49]
	v_mov_b64_e32 v[48:49], v[242:243]
	v_mov_b64_e32 v[50:51], v[244:245]
	v_mov_b64_e32 v[58:59], v[246:247]
	v_mov_b64_e32 v[60:61], v[248:249]
	v_mov_b64_e32 v[62:63], v[250:251]
	v_mov_b64_e32 v[64:65], v[252:253]
	s_nop 0
	v_pk_mul_f32 v[42:43], v[42:43], v[58:59]
	s_nop 0
	v_pk_fma_f32 v[42:43], v[54:55], v[48:49], v[42:43]
	s_nop 0
	v_pk_fma_f32 v[38:39], v[38:39], v[62:63], v[42:43]
	s_nop 0
	v_mul_f32_e32 v0, 0xbfb8aa3b, v38
	v_exp_f32_e32 v42, v0
	v_mul_f32_e32 v0, 0xbfb8aa3b, v39
	v_exp_f32_e32 v43, v0
	s_nop 0
	v_pk_add_f32 v[42:43], v[42:43], 1.0 op_sel_hi:[1,0]
	s_nop 0
	v_div_scale_f32 v0, s[0:1], v43, v43, v39
	v_rcp_f32_e32 v48, v0
	s_nop 0
	v_fma_f32 v49, -v0, v48, 1.0
	v_fmac_f32_e32 v48, v49, v48
	v_div_scale_f32 v49, vcc, v39, v43, v39
	v_mul_f32_e32 v52, v49, v48
	v_fma_f32 v53, -v0, v52, v49
	v_fmac_f32_e32 v52, v53, v48
	v_fma_f32 v0, -v0, v52, v49
	v_div_fmas_f32 v0, v0, v48, v52
	v_div_fixup_f32 v39, v0, v43, v39
	v_div_scale_f32 v0, s[0:1], v42, v42, v38
	v_rcp_f32_e32 v43, v0
	s_nop 0
	v_fma_f32 v48, -v0, v43, 1.0
	v_fmac_f32_e32 v43, v48, v43
	v_div_scale_f32 v48, vcc, v38, v42, v38
	v_mul_f32_e32 v49, v48, v43
	v_fma_f32 v52, -v0, v49, v48
	v_fmac_f32_e32 v49, v52, v43
	v_fma_f32 v0, -v0, v49, v48
	v_div_fmas_f32 v0, v0, v43, v49
	v_div_fixup_f32 v38, v0, v42, v38
	v_pk_mul_f32 v[34:35], v[34:35], v[38:39]
	v_pk_mul_f32 v[38:39], v[44:45], v[60:61]
	v_cvt_pk_bf16_f32 v48, v34, v35
	v_pk_fma_f32 v[38:39], v[56:57], v[50:51], v[38:39]
	v_mad_i64_i32 v[34:35], s[0:1], v174, s90, v[102:103]
	v_pk_fma_f32 v[38:39], v[40:41], v[64:65], v[38:39]
	v_add_u32_e32 v64, s97, v130
	v_mul_f32_e32 v0, 0xbfb8aa3b, v38
	v_exp_f32_e32 v40, v0
	v_mul_f32_e32 v0, 0xbfb8aa3b, v39
	v_exp_f32_e32 v41, v0
	s_nop 0
	v_pk_add_f32 v[40:41], v[40:41], 1.0 op_sel_hi:[1,0]
	s_nop 0
	v_div_scale_f32 v0, s[0:1], v41, v41, v39
	v_rcp_f32_e32 v42, v0
	s_nop 0
	v_fma_f32 v43, -v0, v42, 1.0
	v_fmac_f32_e32 v42, v43, v42
	v_div_scale_f32 v43, vcc, v39, v41, v39
	v_mul_f32_e32 v44, v43, v42
	v_fma_f32 v45, -v0, v44, v43
	v_fmac_f32_e32 v44, v45, v42
	v_fma_f32 v0, -v0, v44, v43
	v_div_fmas_f32 v0, v0, v42, v44
	v_div_fixup_f32 v39, v0, v41, v39
	v_div_scale_f32 v0, s[0:1], v40, v40, v38
	v_rcp_f32_e32 v41, v0
	s_movk_i32 s0, 0x3fff
	v_cmp_lt_i32_e64 s[0:1], s0, v64
	v_fma_f32 v42, -v0, v41, 1.0
	v_fmac_f32_e32 v41, v42, v41
	v_div_scale_f32 v42, vcc, v38, v40, v38
	v_mul_f32_e32 v43, v42, v41
	v_fma_f32 v44, -v0, v43, v42
	v_fmac_f32_e32 v43, v44, v41
	v_fma_f32 v0, -v0, v43, v42
	v_div_fmas_f32 v0, v0, v41, v43
	v_div_fixup_f32 v38, v0, v40, v38
	v_pk_mul_f32 v[36:37], v[36:37], v[38:39]
	s_nop 0
	v_cvt_pk_bf16_f32 v49, v36, v37
	global_store_dwordx4 v[34:35], v[46:49], off
	s_and_saveexec_b64 s[54:55], s[0:1]
	s_xor_b64 s[54:55], exec, s[54:55]
	v_add_u32_e32 v0, 0xffffc000, v64
	v_lshrrev_b32_e32 v38, 3, v0
	s_or_saveexec_b64 s[54:55], s[54:55]
	v_mov_b32_e32 v36, 0x80
	v_mov_b32_e32 v0, 6
	v_mov_b32_e32 v37, 7
	v_mov_b64_e32 v[42:43], 0x27bb440
	s_xor_b64 exec, exec, s[54:55]
	v_ashrrev_i32_e32 v38, 11, v64
	v_mov_b32_e32 v36, 8
	v_mov_b32_e32 v0, 0x7fe
	v_mov_b32_e32 v37, 0x7ff
	v_mov_b64_e32 v[42:43], 0x1255040
	s_or_b64 exec, exec, s[54:55]
	v_lshl_add_u64 v[34:35], s[48:49], 0, v[92:93]
	s_and_saveexec_b64 s[54:55], s[50:51]
	s_cbranch_execz .LBB0_253
	v_cvt_pk_bf16_f32 v40, v30, v31
	v_cvt_pk_bf16_f32 v41, v32, v33
	v_lshl_add_u64 v[44:45], v[104:105], 1, v[34:35]
	global_store_dwordx2 v[44:45], v[40:41], off

.LBB0_255:
	s_or_b64 exec, exec, s[56:57]
	v_cmp_ne_u32_e64 s[56:57], 0, v40
	s_and_saveexec_b64 s[58:59], s[56:57]
	s_xor_b64 s[58:59], exec, s[58:59]
	ds_read_b128 v[42:45], v141
	s_or_saveexec_b64 s[58:59], s[58:59]
	v_add_u32_e32 v46, s92, v38
	v_mad_i64_i32 v[38:39], s[60:61], v46, s78, 0
	s_xor_b64 exec, exec, s[58:59]
	s_cbranch_execz .LBB0_261
	s_waitcnt lgkmcnt(0)
	v_mov_b32_e32 v43, 0
	v_mov_b32_e32 v42, 0
	v_mov_b32_e32 v45, 0
	v_mov_b32_e32 v44, 0
	s_and_saveexec_b64 s[60:61], s[0:1]
	s_cbranch_execz .LBB0_260
	v_readlane_b32 s4, v240, 42
	v_readlane_b32 s5, v240, 43
	v_readlane_b32 s6, v240, 44
	v_readlane_b32 s7, v240, 45
	v_lshl_add_u64 v[42:43], s[4:5], 0, v[38:39]
	v_lshl_add_u64 v[42:43], v[104:105], 2, v[42:43]
	v_add_co_u32_e32 v42, vcc, 0x2000, v42
	v_readlane_b32 s8, v240, 46
	s_nop 0
	v_addc_co_u32_e32 v43, vcc, 0, v43, vcc
	global_load_dwordx4 v[42:45], v[42:43], off offset:3072 nt
	s_waitcnt vmcnt(0)
	v_readlane_b32 s9, v240, 47
	v_readlane_b32 s10, v240, 48
	v_readlane_b32 s11, v240, 49
	v_readlane_b32 s12, v240, 50
	v_readlane_b32 s13, v240, 51
	v_readlane_b32 s14, v240, 52
	v_readlane_b32 s15, v240, 53
	v_readlane_b32 s16, v240, 54
	v_readlane_b32 s17, v240, 55
	v_readlane_b32 s18, v240, 56
	v_readlane_b32 s19, v240, 57

.LBB0_261:
	s_or_b64 exec, exec, s[58:59]
	v_ashrrev_i32_e32 v47, 31, v46
	v_mov_b32_e32 v41, v1
	v_cmp_gt_u32_e64 s[58:59], 2, v40
	v_lshl_add_u64 v[40:41], v[46:47], 1, v[40:41]
	v_mad_u64_u32 v[62:63], s[60:61], v40, s79, 0
	v_mad_i32_i24 v63, v41, s79, v63
	s_and_saveexec_b64 s[60:61], s[58:59]
	s_xor_b64 s[60:61], exec, s[60:61]
	s_cbranch_execz .LBB0_265
	v_mov_b32_e32 v49, 0
	v_mov_b32_e32 v48, 0
	v_mov_b32_e32 v47, 0
	v_mov_b32_e32 v46, 0
	s_and_saveexec_b64 s[74:75], s[0:1]
	s_cbranch_execz .LBB0_264
	v_readlane_b32 s4, v240, 42
	v_readlane_b32 s5, v240, 43
	v_readlane_b32 s6, v240, 44
	v_readlane_b32 s7, v240, 45
	v_lshl_add_u64 v[40:41], s[4:5], 0, v[62:63]
	v_lshl_add_u64 v[40:41], v[104:105], 2, v[40:41]
	global_load_dwordx4 v[46:49], v[40:41], off nt
	s_waitcnt vmcnt(0)
	v_readlane_b32 s8, v240, 46
	v_readlane_b32 s9, v240, 47
	v_readlane_b32 s10, v240, 48
	v_readlane_b32 s11, v240, 49
	v_readlane_b32 s12, v240, 50
	v_readlane_b32 s13, v240, 51
	v_readlane_b32 s14, v240, 52
	v_readlane_b32 s15, v240, 53
	v_readlane_b32 s16, v240, 54
	v_readlane_b32 s17, v240, 55
	v_readlane_b32 s18, v240, 56
	v_readlane_b32 s19, v240, 57

.LBB0_265:
	s_andn2_saveexec_b64 s[60:61], s[60:61]
	s_cbranch_execz .LBB0_267
	s_nop 0
	ds_read_b128 v[46:49], v142
.LBB0_267:
	s_or_b64 exec, exec, s[60:61]
	v_mov_b64_e32 v[50:51], v[226:227]
	v_mov_b64_e32 v[52:53], v[228:229]
	v_mov_b64_e32 v[58:59], v[230:231]
	v_mov_b64_e32 v[60:61], v[232:233]
	v_mov_b64_e32 v[54:55], v[234:235]
	v_mov_b64_e32 v[56:57], v[236:237]
	s_and_saveexec_b64 s[60:61], s[50:51]
	s_cbranch_execz .LBB0_269
	v_cvt_pk_bf16_f32 v40, v22, v23
	v_cvt_pk_bf16_f32 v41, v24, v25
	v_lshl_add_u64 v[34:35], v[106:107], 1, v[34:35]
	global_store_dwordx2 v[34:35], v[40:41], off offset:8
	s_or_b64 exec, exec, s[60:61]
	s_and_saveexec_b64 s[60:61], s[54:55]
	s_cbranch_execz .LBB0_271
	s_branch .LBB0_270

.LBB0_274:
	v_mov_b32_e32 v41, 0
	v_mov_b32_e32 v40, 0
	v_mov_b32_e32 v39, 0
	v_mov_b32_e32 v38, 0
	s_and_saveexec_b64 s[56:57], s[0:1]
	s_cbranch_execz .LBB0_276
	v_readlane_b32 s4, v240, 42
	v_readlane_b32 s5, v240, 43
	v_readlane_b32 s6, v240, 44
	v_readlane_b32 s7, v240, 45
	v_lshl_add_u64 v[38:39], s[4:5], 0, v[62:63]
	v_lshl_add_u64 v[38:39], v[106:107], 2, v[38:39]
	global_load_dwordx4 v[38:41], v[38:39], off offset:16 nt
	s_waitcnt vmcnt(0)
	v_readlane_b32 s8, v240, 46
	v_readlane_b32 s9, v240, 47
	v_readlane_b32 s10, v240, 48
	v_readlane_b32 s11, v240, 49
	v_readlane_b32 s12, v240, 50
	v_readlane_b32 s13, v240, 51
	v_readlane_b32 s14, v240, 52
	v_readlane_b32 s15, v240, 53
	v_readlane_b32 s16, v240, 54
	v_readlane_b32 s17, v240, 55
	v_readlane_b32 s18, v240, 56
	v_readlane_b32 s19, v240, 57

.LBB0_278:
	s_waitcnt lgkmcnt(0)
	v_mov_b32_e32 v35, 0
	v_mov_b32_e32 v34, 0
	v_mov_b32_e32 v37, 0
	v_mov_b32_e32 v36, 0
	s_and_saveexec_b64 s[56:57], s[0:1]
	s_cbranch_execz .LBB0_280
	v_readlane_b32 s4, v240, 42
	v_readlane_b32 s5, v240, 43
	v_readlane_b32 s6, v240, 44
	v_readlane_b32 s7, v240, 45
	v_lshl_add_u64 v[34:35], s[4:5], 0, v[38:39]
	v_lshl_add_u64 v[34:35], v[108:109], 2, v[34:35]
	v_add_co_u32_e32 v34, vcc, 0x2000, v34
	v_readlane_b32 s8, v240, 46
	s_nop 0
	v_addc_co_u32_e32 v35, vcc, 0, v35, vcc
	global_load_dwordx4 v[34:37], v[34:35], off offset:3072 nt
	s_waitcnt vmcnt(0)
	v_readlane_b32 s9, v240, 47
	v_readlane_b32 s10, v240, 48
	v_readlane_b32 s11, v240, 49
	v_readlane_b32 s12, v240, 50
	v_readlane_b32 s13, v240, 51
	v_readlane_b32 s14, v240, 52
	v_readlane_b32 s15, v240, 53
	v_readlane_b32 s16, v240, 54
	v_readlane_b32 s17, v240, 55
	v_readlane_b32 s18, v240, 56
	v_readlane_b32 s19, v240, 57

.LBB0_282:
	s_nop 0
	ds_read_b128 v[38:41], v164
.LBB0_283:
	s_or_b64 exec, exec, s[0:1]
	s_waitcnt lgkmcnt(0)
	v_pk_mul_f32 v[42:43], v[42:43], v[58:59]
	s_nop 0
	v_pk_fma_f32 v[42:43], v[46:47], v[50:51], v[42:43]
	s_nop 0
	v_pk_fma_f32 v[30:31], v[30:31], v[54:55], v[42:43]
	s_nop 0
	v_mul_f32_e32 v0, 0xbfb8aa3b, v30
	v_exp_f32_e32 v42, v0
	v_mul_f32_e32 v0, 0xbfb8aa3b, v31
	v_exp_f32_e32 v43, v0
	s_nop 0
	v_pk_add_f32 v[42:43], v[42:43], 1.0 op_sel_hi:[1,0]
	s_nop 0
	v_div_scale_f32 v0, s[0:1], v43, v43, v31
	v_rcp_f32_e32 v46, v0
	s_nop 0
	v_fma_f32 v47, -v0, v46, 1.0
	v_fmac_f32_e32 v46, v47, v46
	v_div_scale_f32 v47, vcc, v31, v43, v31
	v_mul_f32_e32 v50, v47, v46
	v_fma_f32 v51, -v0, v50, v47
	v_fmac_f32_e32 v50, v51, v46
	v_fma_f32 v0, -v0, v50, v47
	v_div_fmas_f32 v0, v0, v46, v50
	v_div_fixup_f32 v31, v0, v43, v31
	v_div_scale_f32 v0, s[0:1], v42, v42, v30
	v_rcp_f32_e32 v43, v0
	s_nop 0
	v_fma_f32 v46, -v0, v43, 1.0
	v_fmac_f32_e32 v43, v46, v43
	v_div_scale_f32 v46, vcc, v30, v42, v30
	v_mul_f32_e32 v47, v46, v43
	v_fma_f32 v50, -v0, v47, v46
	v_fmac_f32_e32 v47, v50, v43
	v_fma_f32 v0, -v0, v47, v46
	v_div_fmas_f32 v0, v0, v43, v47
	v_div_fixup_f32 v30, v0, v42, v30
	v_pk_mul_f32 v[26:27], v[26:27], v[30:31]
	v_pk_mul_f32 v[30:31], v[44:45], v[60:61]
	v_cvt_pk_bf16_f32 v26, v26, v27
	v_pk_fma_f32 v[30:31], v[48:49], v[52:53], v[30:31]
	s_nop 0
	v_pk_fma_f32 v[30:31], v[32:33], v[56:57], v[30:31]
	s_nop 0
	v_mul_f32_e32 v0, 0xbfb8aa3b, v30
	v_exp_f32_e32 v32, v0
	v_mul_f32_e32 v0, 0xbfb8aa3b, v31
	v_exp_f32_e32 v33, v0
	s_nop 0
	v_pk_add_f32 v[32:33], v[32:33], 1.0 op_sel_hi:[1,0]
	s_nop 0
	v_div_scale_f32 v0, s[0:1], v33, v33, v31
	v_rcp_f32_e32 v42, v0
	s_nop 0
	v_fma_f32 v43, -v0, v42, 1.0
	v_fmac_f32_e32 v42, v43, v42
	v_div_scale_f32 v43, vcc, v31, v33, v31
	v_mul_f32_e32 v44, v43, v42
	v_fma_f32 v45, -v0, v44, v43
	v_fmac_f32_e32 v44, v45, v42
	v_fma_f32 v0, -v0, v44, v43
	v_div_fmas_f32 v0, v0, v42, v44
	v_div_fixup_f32 v31, v0, v33, v31
	v_div_scale_f32 v0, s[0:1], v32, v32, v30
	v_rcp_f32_e32 v33, v0
	s_nop 0
	v_fma_f32 v42, -v0, v33, 1.0
	v_fmac_f32_e32 v33, v42, v33
	v_div_scale_f32 v42, vcc, v30, v32, v30
	v_mul_f32_e32 v43, v42, v33
	v_fma_f32 v44, -v0, v43, v42
	v_fmac_f32_e32 v43, v44, v33
	v_fma_f32 v0, -v0, v43, v42
	v_div_fmas_f32 v0, v0, v33, v43
	v_div_fixup_f32 v30, v0, v32, v30
	v_pk_mul_f32 v[28:29], v[28:29], v[30:31]
	s_nop 0
	v_cvt_pk_bf16_f32 v27, v28, v29
	v_mov_b64_e32 v[28:29], v[242:243]
	v_mov_b64_e32 v[30:31], v[244:245]
	v_mov_b64_e32 v[42:43], v[246:247]
	v_mov_b64_e32 v[44:45], v[248:249]
	v_mov_b64_e32 v[46:47], v[250:251]
	v_mov_b64_e32 v[48:49], v[252:253]
	s_nop 0
	v_pk_mul_f32 v[32:33], v[34:35], v[42:43]
	s_nop 0
	v_pk_fma_f32 v[28:29], v[38:39], v[28:29], v[32:33]
	s_nop 0
	v_pk_fma_f32 v[22:23], v[22:23], v[46:47], v[28:29]
	s_nop 0
	v_mul_f32_e32 v0, 0xbfb8aa3b, v22
	v_exp_f32_e32 v28, v0
	v_mul_f32_e32 v0, 0xbfb8aa3b, v23
	v_exp_f32_e32 v29, v0
	s_nop 0
	v_pk_add_f32 v[28:29], v[28:29], 1.0 op_sel_hi:[1,0]
	s_nop 0
	v_div_scale_f32 v0, s[0:1], v29, v29, v23
	v_rcp_f32_e32 v32, v0
	s_nop 0
	v_fma_f32 v33, -v0, v32, 1.0
	v_fmac_f32_e32 v32, v33, v32
	v_div_scale_f32 v33, vcc, v23, v29, v23
	v_mul_f32_e32 v34, v33, v32
	v_fma_f32 v35, -v0, v34, v33
	v_fmac_f32_e32 v34, v35, v32
	v_fma_f32 v0, -v0, v34, v33
	v_div_fmas_f32 v0, v0, v32, v34
	v_div_fixup_f32 v23, v0, v29, v23
	v_div_scale_f32 v0, s[0:1], v28, v28, v22
	v_rcp_f32_e32 v29, v0
	s_nop 0
	v_fma_f32 v32, -v0, v29, 1.0
	v_fmac_f32_e32 v29, v32, v29
	v_div_scale_f32 v32, vcc, v22, v28, v22
	v_mul_f32_e32 v33, v32, v29
	v_fma_f32 v34, -v0, v33, v32
	v_fmac_f32_e32 v33, v34, v29
	v_fma_f32 v0, -v0, v33, v32
	v_div_fmas_f32 v0, v0, v29, v33
	v_div_fixup_f32 v22, v0, v28, v22
	v_pk_mul_f32 v[18:19], v[18:19], v[22:23]
	v_pk_mul_f32 v[22:23], v[36:37], v[44:45]
	s_nop 0
	v_pk_fma_f32 v[22:23], v[40:41], v[30:31], v[22:23]
	s_nop 0
	v_pk_fma_f32 v[22:23], v[24:25], v[48:49], v[22:23]
	v_add_u32_e32 v48, s97, v131
	v_mul_f32_e32 v0, 0xbfb8aa3b, v22
	v_exp_f32_e32 v24, v0
	v_mul_f32_e32 v0, 0xbfb8aa3b, v23
	v_exp_f32_e32 v25, v0
	s_nop 0
	v_pk_add_f32 v[24:25], v[24:25], 1.0 op_sel_hi:[1,0]
	s_nop 0
	v_div_scale_f32 v0, s[0:1], v25, v25, v23
	v_rcp_f32_e32 v28, v0
	s_nop 0
	v_fma_f32 v29, -v0, v28, 1.0
	v_fmac_f32_e32 v28, v29, v28
	v_div_scale_f32 v29, vcc, v23, v25, v23
	v_mul_f32_e32 v30, v29, v28
	v_fma_f32 v31, -v0, v30, v29
	v_fmac_f32_e32 v30, v31, v28
	v_fma_f32 v0, -v0, v30, v29
	v_div_fmas_f32 v0, v0, v28, v30
	v_div_fixup_f32 v23, v0, v25, v23
	v_div_scale_f32 v0, s[0:1], v24, v24, v22
	v_rcp_f32_e32 v25, v0
	s_nop 0
	v_fma_f32 v28, -v0, v25, 1.0
	v_fmac_f32_e32 v25, v28, v25
	v_div_scale_f32 v28, vcc, v22, v24, v22
	v_mul_f32_e32 v29, v28, v25
	v_fma_f32 v30, -v0, v29, v28
	v_fmac_f32_e32 v29, v30, v25
	v_fma_f32 v0, -v0, v29, v28
	v_div_fmas_f32 v0, v0, v25, v29
	v_div_fixup_f32 v22, v0, v24, v22
	v_cvt_pk_bf16_f32 v28, v18, v19
	v_mad_i64_i32 v[18:19], s[0:1], v64, s90, v[102:103]
	v_pk_mul_f32 v[20:21], v[20:21], v[22:23]
	s_movk_i32 s0, 0x3fff
	v_cvt_pk_bf16_f32 v29, v20, v21
	v_cmp_lt_i32_e64 s[0:1], s0, v48
	global_store_dwordx4 v[18:19], v[26:29], off
	s_and_saveexec_b64 s[54:55], s[0:1]
	s_xor_b64 s[54:55], exec, s[54:55]
	v_add_u32_e32 v0, 0xffffc000, v48
	v_lshrrev_b32_e32 v22, 3, v0
	s_or_saveexec_b64 s[54:55], s[54:55]
	v_mov_b32_e32 v23, 0x80
	v_mov_b32_e32 v0, 6
	v_mov_b32_e32 v24, 7
	v_mov_b64_e32 v[26:27], 0x27bb440
	s_xor_b64 exec, exec, s[54:55]
	v_ashrrev_i32_e32 v22, 11, v48
	v_mov_b32_e32 v23, 8
	v_mov_b32_e32 v0, 0x7fe
	v_mov_b32_e32 v24, 0x7ff
	v_mov_b64_e32 v[26:27], 0x1255040
	s_or_b64 exec, exec, s[54:55]
	v_lshl_add_u64 v[18:19], s[48:49], 0, v[96:97]
	s_mov_b64 s[4:5], 0x1600
	v_lshl_add_u64 v[20:21], s[48:49], 0, v[94:95]
	v_lshl_add_u64 v[18:19], v[18:19], 0, s[4:5]
	s_and_saveexec_b64 s[48:49], s[52:53]
	s_movk_i32 s76, 0x1600
	s_cbranch_execz .LBB0_290
	v_readlane_b32 s4, v239, 63
	v_cvt_pk_bf16_f32 v28, v14, v15
	v_cvt_pk_bf16_f32 v29, v16, v17
	v_lshl_add_u64 v[30:31], v[104:105], 1, v[20:21]
	v_readlane_b32 s5, v238, 0
	global_store_dwordx2 v[30:31], v[28:29], off
	s_and_b64 exec, exec, s[4:5]
	s_cbranch_execz .LBB0_290
	v_cvt_pk_bf16_f32 v28, v10, v11
	v_cvt_pk_bf16_f32 v29, v12, v13
	v_lshl_add_u64 v[30:31], v[104:105], 1, v[18:19]
	global_store_dwordx2 v[30:31], v[28:29], off

.LBB0_292:
	s_or_b64 exec, exec, s[54:55]
	v_cmp_ne_u32_e64 s[56:57], 0, v30
	s_and_saveexec_b64 s[54:55], s[56:57]
	s_xor_b64 s[54:55], exec, s[54:55]
	ds_read_b128 v[26:29], v165
	s_or_saveexec_b64 s[54:55], s[54:55]
	v_add_u32_e32 v32, s92, v22
	v_mad_i64_i32 v[22:23], s[58:59], v32, s78, 0
	s_xor_b64 exec, exec, s[54:55]
	s_cbranch_execz .LBB0_298
	s_waitcnt lgkmcnt(0)
	v_mov_b32_e32 v27, 0
	v_mov_b32_e32 v26, 0
	v_mov_b32_e32 v29, 0
	v_mov_b32_e32 v28, 0
	s_and_saveexec_b64 s[58:59], s[0:1]
	s_cbranch_execz .LBB0_297
	v_readlane_b32 s4, v240, 42
	v_readlane_b32 s5, v240, 43
	v_readlane_b32 s6, v240, 44
	v_readlane_b32 s7, v240, 45
	v_lshl_add_u64 v[26:27], s[4:5], 0, v[22:23]
	v_lshl_add_u64 v[26:27], v[104:105], 2, v[26:27]
	v_add_co_u32_e32 v26, vcc, 0x2000, v26
	v_readlane_b32 s8, v240, 46
	s_nop 0
	v_addc_co_u32_e32 v27, vcc, 0, v27, vcc
	global_load_dwordx4 v[26:29], v[26:27], off offset:3072 nt
	s_waitcnt vmcnt(0)
	v_readlane_b32 s9, v240, 47
	v_readlane_b32 s10, v240, 48
	v_readlane_b32 s11, v240, 49
	v_readlane_b32 s12, v240, 50
	v_readlane_b32 s13, v240, 51
	v_readlane_b32 s14, v240, 52
	v_readlane_b32 s15, v240, 53
	v_readlane_b32 s16, v240, 54
	v_readlane_b32 s17, v240, 55
	v_readlane_b32 s18, v240, 56
	v_readlane_b32 s19, v240, 57

.LBB0_298:
	s_or_b64 exec, exec, s[54:55]
	v_ashrrev_i32_e32 v33, 31, v32
	v_mov_b32_e32 v31, v1
	v_cmp_gt_u32_e64 s[58:59], 2, v30
	v_lshl_add_u64 v[30:31], v[32:33], 1, v[30:31]
	v_mad_u64_u32 v[46:47], s[54:55], v30, s79, 0
	v_mad_i32_i24 v47, v31, s79, v47
	s_and_saveexec_b64 s[54:55], s[58:59]
	s_xor_b64 s[54:55], exec, s[54:55]
	s_cbranch_execz .LBB0_302
	v_mov_b32_e32 v33, 0
	v_mov_b32_e32 v32, 0
	v_mov_b32_e32 v31, 0
	v_mov_b32_e32 v30, 0
	s_and_saveexec_b64 s[60:61], s[0:1]
	s_cbranch_execz .LBB0_301
	v_readlane_b32 s4, v240, 42
	v_readlane_b32 s5, v240, 43
	v_readlane_b32 s6, v240, 44
	v_readlane_b32 s7, v240, 45
	v_lshl_add_u64 v[30:31], s[4:5], 0, v[46:47]
	v_lshl_add_u64 v[30:31], v[104:105], 2, v[30:31]
	global_load_dwordx4 v[30:33], v[30:31], off nt
	s_waitcnt vmcnt(0)
	v_readlane_b32 s8, v240, 46
	v_readlane_b32 s9, v240, 47
	v_readlane_b32 s10, v240, 48
	v_readlane_b32 s11, v240, 49
	v_readlane_b32 s12, v240, 50
	v_readlane_b32 s13, v240, 51
	v_readlane_b32 s14, v240, 52
	v_readlane_b32 s15, v240, 53
	v_readlane_b32 s16, v240, 54
	v_readlane_b32 s17, v240, 55
	v_readlane_b32 s18, v240, 56
	v_readlane_b32 s19, v240, 57

.LBB0_302:
	s_andn2_saveexec_b64 s[54:55], s[54:55]
	s_cbranch_execz .LBB0_304
	s_nop 0
	ds_read_b128 v[30:33], v166
.LBB0_304:
	s_or_b64 exec, exec, s[54:55]
	v_mov_b64_e32 v[34:35], v[226:227]
	v_mov_b64_e32 v[36:37], v[228:229]
	v_mov_b64_e32 v[42:43], v[230:231]
	v_mov_b64_e32 v[44:45], v[232:233]
	v_mov_b64_e32 v[38:39], v[234:235]
	v_mov_b64_e32 v[40:41], v[236:237]
	s_and_saveexec_b64 s[54:55], s[52:53]
	s_cbranch_execz .LBB0_307
	v_readlane_b32 s4, v239, 63
	v_cvt_pk_bf16_f32 v50, v6, v7
	v_cvt_pk_bf16_f32 v51, v8, v9
	v_lshl_add_u64 v[20:21], v[106:107], 1, v[20:21]
	v_readlane_b32 s5, v238, 0
	global_store_dwordx2 v[20:21], v[50:51], off offset:8
	s_and_b64 exec, exec, s[4:5]
	s_cbranch_execz .LBB0_307
	v_cvt_pk_bf16_f32 v20, v2, v3
	v_cvt_pk_bf16_f32 v21, v4, v5
	v_lshl_add_u64 v[18:19], v[108:109], 1, v[18:19]
	global_store_dwordx2 v[18:19], v[20:21], off

.LBB0_312:
	v_mov_b32_e32 v25, 0
	v_mov_b32_e32 v24, 0
	v_mov_b32_e32 v23, 0
	v_mov_b32_e32 v22, 0
	s_and_saveexec_b64 s[54:55], s[0:1]
	s_cbranch_execz .LBB0_314
	v_readlane_b32 s4, v240, 42
	v_readlane_b32 s5, v240, 43
	v_readlane_b32 s6, v240, 44
	v_readlane_b32 s7, v240, 45
	v_lshl_add_u64 v[22:23], s[4:5], 0, v[46:47]
	v_lshl_add_u64 v[22:23], v[106:107], 2, v[22:23]
	global_load_dwordx4 v[22:25], v[22:23], off offset:16 nt
	s_waitcnt vmcnt(0)
	v_readlane_b32 s8, v240, 46
	v_readlane_b32 s9, v240, 47
	v_readlane_b32 s10, v240, 48
	v_readlane_b32 s11, v240, 49
	v_readlane_b32 s12, v240, 50
	v_readlane_b32 s13, v240, 51
	v_readlane_b32 s14, v240, 52
	v_readlane_b32 s15, v240, 53
	v_readlane_b32 s16, v240, 54
	v_readlane_b32 s17, v240, 55
	v_readlane_b32 s18, v240, 56
	v_readlane_b32 s19, v240, 57

.LBB0_316:
	s_waitcnt lgkmcnt(0)
	v_mov_b32_e32 v19, 0
	v_mov_b32_e32 v18, 0
	v_mov_b32_e32 v21, 0
	v_mov_b32_e32 v20, 0
	s_and_saveexec_b64 s[54:55], s[0:1]
	s_cbranch_execz .LBB0_318
	v_readlane_b32 s4, v240, 42
	v_readlane_b32 s5, v240, 43
	v_readlane_b32 s6, v240, 44
	v_readlane_b32 s7, v240, 45
	v_lshl_add_u64 v[18:19], s[4:5], 0, v[22:23]
	v_lshl_add_u64 v[18:19], v[108:109], 2, v[18:19]
	v_add_co_u32_e32 v18, vcc, 0x2000, v18
	v_readlane_b32 s8, v240, 46
	s_nop 0
	v_addc_co_u32_e32 v19, vcc, 0, v19, vcc
	global_load_dwordx4 v[18:21], v[18:19], off offset:3072 nt
	s_waitcnt vmcnt(0)
	v_readlane_b32 s9, v240, 47
	v_readlane_b32 s10, v240, 48
	v_readlane_b32 s11, v240, 49
	v_readlane_b32 s12, v240, 50
	v_readlane_b32 s13, v240, 51
	v_readlane_b32 s14, v240, 52
	v_readlane_b32 s15, v240, 53
	v_readlane_b32 s16, v240, 54
	v_readlane_b32 s17, v240, 55
	v_readlane_b32 s18, v240, 56
	v_readlane_b32 s19, v240, 57

.LBB0_320:
	s_nop 0
	ds_read_b128 v[22:25], v168
	s_branch .LBB0_164
.LBB0_321:
	s_mov_b64 s[34:35], 0x1a40080
	s_mov_b64 s[36:37], 0x1a50080
	s_mov_b64 s[64:65], 0x1a60080
	s_mov_b64 s[66:67], 0x1a70080
	v_readlane_b32 s54, v239, 48
	s_mov_b64 s[0:1], 0
	v_readlane_b32 s91, v239, 50
	v_readlane_b32 s92, v239, 51
	s_movk_i32 s97, 0x3ff
	v_readlane_b32 s55, v239, 49

	.amdhsa_kernel _Z14fwd_megakernel6Paramsii
		.amdhsa_group_segment_fixed_size 0
		.amdhsa_private_segment_fixed_size 0
		.amdhsa_kernarg_size 488
		.amdhsa_user_sgpr_count 2
		.amdhsa_user_sgpr_dispatch_ptr 0
		.amdhsa_user_sgpr_queue_ptr 0
		.amdhsa_user_sgpr_kernarg_segment_ptr 1
		.amdhsa_user_sgpr_dispatch_id 0
		.amdhsa_user_sgpr_kernarg_preload_length 0
		.amdhsa_user_sgpr_kernarg_preload_offset 0
		.amdhsa_user_sgpr_private_segment_size 0
		.amdhsa_uses_dynamic_stack 0
		.amdhsa_enable_private_segment 0
		.amdhsa_system_sgpr_workgroup_id_x 1
		.amdhsa_system_sgpr_workgroup_id_y 0
		.amdhsa_system_sgpr_workgroup_id_z 0
		.amdhsa_system_sgpr_workgroup_info 0
		.amdhsa_system_vgpr_workitem_id 2
		.amdhsa_next_free_vgpr 256
		.amdhsa_next_free_sgpr 100
		.amdhsa_accum_offset 256
		.amdhsa_reserve_vcc 1
		.amdhsa_float_round_mode_32 0
		.amdhsa_float_round_mode_16_64 0
		.amdhsa_float_denorm_mode_32 3
		.amdhsa_float_denorm_mode_16_64 3
		.amdhsa_dx10_clamp 1
		.amdhsa_ieee_mode 1
		.amdhsa_fp16_overflow 0
		.amdhsa_tg_split 0
		.amdhsa_exception_fp_ieee_invalid_op 0
		.amdhsa_exception_fp_denorm_src 0
		.amdhsa_exception_fp_ieee_div_zero 0
		.amdhsa_exception_fp_ieee_overflow 0
		.amdhsa_exception_fp_ieee_underflow 0
		.amdhsa_exception_fp_ieee_inexact 0
		.amdhsa_exception_int_div_zero 0
	.end_amdhsa_kernel

amdhsa.kernels:
  - .agpr_count:     0
    .args:
      - .offset:         0
        .size:           224
        .value_kind:     by_value
      - .offset:         224
        .size:           4
        .value_kind:     by_value
      - .offset:         228
        .size:           4
        .value_kind:     by_value
      - .offset:         232
        .size:           4
        .value_kind:     hidden_block_count_x
      - .offset:         236
        .size:           4
        .value_kind:     hidden_block_count_y
      - .offset:         240
        .size:           4
        .value_kind:     hidden_block_count_z
      - .offset:         244
        .size:           2
        .value_kind:     hidden_group_size_x
      - .offset:         246
        .size:           2
        .value_kind:     hidden_group_size_y
      - .offset:         248
        .size:           2
        .value_kind:     hidden_group_size_z
      - .offset:         250
        .size:           2
        .value_kind:     hidden_remainder_x
      - .offset:         252
        .size:           2
        .value_kind:     hidden_remainder_y
      - .offset:         254
        .size:           2
        .value_kind:     hidden_remainder_z
      - .offset:         272
        .size:           8
        .value_kind:     hidden_global_offset_x
      - .offset:         280
        .size:           8
        .value_kind:     hidden_global_offset_y
      - .offset:         288
        .size:           8
        .value_kind:     hidden_global_offset_z
      - .offset:         296
        .size:           2
        .value_kind:     hidden_grid_dims
      - .offset:         320
        .size:           8
        .value_kind:     hidden_multigrid_sync_arg
      - .offset:         352
        .size:           4
        .value_kind:     hidden_dynamic_lds_size
    .group_segment_fixed_size: 0
    .kernarg_segment_align: 8
    .kernarg_segment_size: 488
    .language:       OpenCL C
    .language_version:
      - 2
      - 0
    .max_flat_workgroup_size: 256
    .name:           _Z14fwd_megakernel6Paramsii
    .private_segment_fixed_size: 0
    .sgpr_count:     106
    .sgpr_spill_count: 195
    .symbol:         _Z14fwd_megakernel6Paramsii.kd
    .uniform_work_group_size: 1
    .uses_dynamic_stack: false
    .vgpr_count:     256
    .vgpr_spill_count: 0
    .wavefront_size: 64
